# all transpose ladders batched (gain, shared-tail and straight forms) + x->bf16 row loop software-pipelined (next row's loads in flight while the current row is reduced/stored)
# speedup vs baseline: 1.0103x; 1.0008x over previous
.Lladder_ng_g0:
	global_load_dword v82, v[78:79], off
	v_or_b32_e32 v10, s25, v5
	v_lshlrev_b32_e32 v10, 14, v10
	v_lshl_add_u64 v[78:79], v[16:17], 0, v[10:11]
	global_load_dword v83, v[78:79], off
	v_or_b32_e32 v10, s25, v13
	v_lshlrev_b32_e32 v10, 14, v10
	v_lshl_add_u64 v[78:79], v[16:17], 0, v[10:11]
	global_load_dword v84, v[78:79], off
	v_or_b32_e32 v10, s25, v21
	v_lshlrev_b32_e32 v10, 14, v10
	v_lshl_add_u64 v[78:79], v[16:17], 0, v[10:11]
	global_load_dword v85, v[78:79], off
	v_or_b32_e32 v10, s25, v23
	v_lshlrev_b32_e32 v10, 14, v10
	v_lshl_add_u64 v[78:79], v[16:17], 0, v[10:11]
	global_load_dword v86, v[78:79], off
	v_or_b32_e32 v10, s25, v25
	v_lshlrev_b32_e32 v10, 14, v10
	v_lshl_add_u64 v[78:79], v[16:17], 0, v[10:11]
	global_load_dword v87, v[78:79], off
	v_or_b32_e32 v10, s25, v27
	v_lshlrev_b32_e32 v10, 14, v10
	v_lshl_add_u64 v[78:79], v[16:17], 0, v[10:11]
	global_load_dword v88, v[78:79], off
	v_or_b32_e32 v10, s25, v29
	v_lshlrev_b32_e32 v10, 14, v10
	v_lshl_add_u64 v[78:79], v[16:17], 0, v[10:11]
	global_load_dword v89, v[78:79], off
	v_or_b32_e32 v10, s25, v31
	v_lshlrev_b32_e32 v10, 14, v10
	v_lshl_add_u64 v[78:79], v[16:17], 0, v[10:11]
	global_load_dword v90, v[78:79], off
	v_or_b32_e32 v10, s25, v33
	v_lshlrev_b32_e32 v10, 14, v10
	v_lshl_add_u64 v[78:79], v[16:17], 0, v[10:11]
	global_load_dword v91, v[78:79], off
	v_or_b32_e32 v10, s25, v35
	v_lshlrev_b32_e32 v10, 14, v10
	v_lshl_add_u64 v[78:79], v[16:17], 0, v[10:11]
	global_load_dword v92, v[78:79], off
	v_or_b32_e32 v10, s25, v37
	v_lshlrev_b32_e32 v10, 14, v10
	v_lshl_add_u64 v[78:79], v[16:17], 0, v[10:11]
	global_load_dword v93, v[78:79], off
	v_or_b32_e32 v10, s25, v39
	v_lshlrev_b32_e32 v10, 14, v10
	v_lshl_add_u64 v[78:79], v[16:17], 0, v[10:11]
	global_load_dword v94, v[78:79], off
	v_or_b32_e32 v10, s25, v41
	v_lshlrev_b32_e32 v10, 14, v10
	v_lshl_add_u64 v[78:79], v[16:17], 0, v[10:11]
	global_load_dword v95, v[78:79], off
	v_or_b32_e32 v10, s25, v43
	v_lshlrev_b32_e32 v10, 14, v10
	v_lshl_add_u64 v[78:79], v[16:17], 0, v[10:11]
	global_load_dword v96, v[78:79], off
	v_or_b32_e32 v10, s25, v45
	v_lshlrev_b32_e32 v10, 14, v10
	v_lshl_add_u64 v[78:79], v[16:17], 0, v[10:11]
	global_load_dword v97, v[78:79], off
	v_or_b32_e32 v10, s25, v47
	v_lshlrev_b32_e32 v10, 14, v10
	v_lshl_add_u64 v[78:79], v[16:17], 0, v[10:11]
	global_load_dword v98, v[78:79], off
	v_or_b32_e32 v10, s25, v49
	v_lshlrev_b32_e32 v10, 14, v10
	v_lshl_add_u64 v[78:79], v[16:17], 0, v[10:11]
	global_load_dword v99, v[78:79], off
	v_or_b32_e32 v10, s25, v51
	v_lshlrev_b32_e32 v10, 14, v10
	v_lshl_add_u64 v[78:79], v[16:17], 0, v[10:11]
	global_load_dword v100, v[78:79], off
	v_or_b32_e32 v10, s25, v61
	v_lshlrev_b32_e32 v10, 14, v10
	v_lshl_add_u64 v[78:79], v[16:17], 0, v[10:11]
	global_load_dword v101, v[78:79], off
	v_or_b32_e32 v10, s25, v62
	v_lshlrev_b32_e32 v10, 14, v10
	v_lshl_add_u64 v[78:79], v[16:17], 0, v[10:11]
	global_load_dword v102, v[78:79], off
	v_or_b32_e32 v10, s25, v63
	v_lshlrev_b32_e32 v10, 14, v10
	v_lshl_add_u64 v[78:79], v[16:17], 0, v[10:11]
	global_load_dword v103, v[78:79], off
	v_or_b32_e32 v10, s25, v64
	v_lshlrev_b32_e32 v10, 14, v10
	v_lshl_add_u64 v[78:79], v[16:17], 0, v[10:11]
	global_load_dword v104, v[78:79], off
	v_or_b32_e32 v10, s25, v65
	v_lshlrev_b32_e32 v10, 14, v10
	v_lshl_add_u64 v[78:79], v[16:17], 0, v[10:11]
	global_load_dword v105, v[78:79], off
	v_or_b32_e32 v10, s25, v66
	v_lshlrev_b32_e32 v10, 14, v10
	v_lshl_add_u64 v[78:79], v[16:17], 0, v[10:11]
	global_load_dword v106, v[78:79], off
	v_or_b32_e32 v10, s25, v67
	v_lshlrev_b32_e32 v10, 14, v10
	v_lshl_add_u64 v[78:79], v[16:17], 0, v[10:11]
	global_load_dword v107, v[78:79], off
	v_or_b32_e32 v10, s25, v68
	v_lshlrev_b32_e32 v10, 14, v10
	v_lshl_add_u64 v[80:81], v[16:17], 0, v[10:11]
	global_load_dword v108, v[80:81], off
	v_or_b32_e32 v10, s25, v69
	v_lshlrev_b32_e32 v10, 14, v10
	v_lshl_add_u64 v[78:79], v[16:17], 0, v[10:11]
	global_load_dword v109, v[78:79], off
	v_or_b32_e32 v10, s25, v70
	v_lshlrev_b32_e32 v10, 14, v10
	v_lshl_add_u64 v[80:81], v[16:17], 0, v[10:11]
	global_load_dword v110, v[80:81], off
	v_or_b32_e32 v10, s25, v71
	v_lshlrev_b32_e32 v10, 14, v10
	v_lshl_add_u64 v[78:79], v[16:17], 0, v[10:11]
	global_load_dword v111, v[78:79], off
	v_or_b32_e32 v10, s25, v72
	v_lshlrev_b32_e32 v10, 14, v10
	v_lshl_add_u64 v[80:81], v[16:17], 0, v[10:11]
	global_load_dword v112, v[80:81], off
	v_or_b32_e32 v10, s25, v73
	v_lshlrev_b32_e32 v10, 14, v10
	v_lshl_add_u64 v[16:17], v[16:17], 0, v[10:11]
	global_load_dword v113, v[16:17], off
	s_waitcnt vmcnt(0)
	v_add_u32_e32 v114, v1, v3
	ds_write_b32 v114, v82
	v_add_lshl_u32 v115, s25, v6, 2
	v_add_u32_e32 v116, v1, v9
	ds_write_b32 v116, v83
	v_add_u32_e32 v117, v1, v20
	ds_write_b32 v117, v84
	v_add_u32_e32 v118, v1, v22
	ds_write_b32 v118, v85
	v_add_u32_e32 v119, v1, v24
	ds_write_b32 v119, v86
	v_add_u32_e32 v120, v1, v26
	ds_write_b32 v120, v87
	v_add_u32_e32 v121, v1, v28
	ds_write_b32 v121, v88
	v_add_u32_e32 v122, v1, v30
	ds_write_b32 v122, v89
	v_add_u32_e32 v123, v1, v32
	ds_write_b32 v123, v90
	v_add_u32_e32 v124, v1, v34
	ds_write_b32 v124, v91
	v_add_u32_e32 v125, v1, v36
	ds_write_b32 v125, v92
	v_add_u32_e32 v126, v1, v38
	ds_write_b32 v126, v93
	v_add_u32_e32 v127, v1, v40
	ds_write_b32 v127, v94
	v_add_u32_e32 v128, v1, v42
	ds_write_b32 v128, v95
	v_add_u32_e32 v129, v1, v44
	ds_write_b32 v129, v96
	v_add_u32_e32 v130, v1, v46
	ds_write_b32 v130, v97
	v_add_u32_e32 v131, v1, v48
	ds_write_b32 v131, v98
	v_add_u32_e32 v132, v1, v50
	ds_write_b32 v132, v99
	v_add_u32_e32 v133, v1, v52
	ds_write_b32 v133, v100
	v_add_u32_e32 v134, v1, v53
	ds_write_b32 v134, v101
	v_add_u32_e32 v135, v1, v54
	ds_write_b32 v135, v102
	v_add_u32_e32 v136, v1, v55
	ds_write_b32 v136, v103
	v_add_u32_e32 v137, v1, v56
	ds_write_b32 v137, v104
	v_add_u32_e32 v138, v1, v57
	ds_write_b32 v138, v105
	v_add_u32_e32 v139, v1, v58
	ds_write_b32 v139, v106
	ds_write_b32 v139, v107 offset:264
	ds_write_b32 v139, v108 offset:528
	ds_write_b32 v139, v109 offset:792
	ds_write_b32 v139, v110 offset:1056
	ds_write_b32 v139, v111 offset:1320
	ds_write_b32 v139, v112 offset:1584
	v_mov_b32_e32 v140, v113
	ds_write_b32 v139, v140 offset:1848

.Lladder_ng_g1:
	global_load_dword v82, v[78:79], off
	v_or_b32_e32 v10, s8, v5
	v_lshlrev_b32_e32 v10, 12, v10
	v_lshl_add_u64 v[78:79], v[16:17], 0, v[10:11]
	global_load_dword v83, v[78:79], off
	v_or_b32_e32 v10, s8, v13
	v_lshlrev_b32_e32 v10, 12, v10
	v_lshl_add_u64 v[78:79], v[16:17], 0, v[10:11]
	global_load_dword v84, v[78:79], off
	v_or_b32_e32 v10, s8, v21
	v_lshlrev_b32_e32 v10, 12, v10
	v_lshl_add_u64 v[78:79], v[16:17], 0, v[10:11]
	global_load_dword v85, v[78:79], off
	v_or_b32_e32 v10, s8, v23
	v_lshlrev_b32_e32 v10, 12, v10
	v_lshl_add_u64 v[78:79], v[16:17], 0, v[10:11]
	global_load_dword v86, v[78:79], off
	v_or_b32_e32 v10, s8, v25
	v_lshlrev_b32_e32 v10, 12, v10
	v_lshl_add_u64 v[78:79], v[16:17], 0, v[10:11]
	global_load_dword v87, v[78:79], off
	v_or_b32_e32 v10, s8, v27
	v_lshlrev_b32_e32 v10, 12, v10
	v_lshl_add_u64 v[78:79], v[16:17], 0, v[10:11]
	global_load_dword v88, v[78:79], off
	v_or_b32_e32 v10, s8, v29
	v_lshlrev_b32_e32 v10, 12, v10
	v_lshl_add_u64 v[78:79], v[16:17], 0, v[10:11]
	global_load_dword v89, v[78:79], off
	v_or_b32_e32 v10, s8, v31
	v_lshlrev_b32_e32 v10, 12, v10
	v_lshl_add_u64 v[78:79], v[16:17], 0, v[10:11]
	global_load_dword v90, v[78:79], off
	v_or_b32_e32 v10, s8, v33
	v_lshlrev_b32_e32 v10, 12, v10
	v_lshl_add_u64 v[78:79], v[16:17], 0, v[10:11]
	global_load_dword v91, v[78:79], off
	v_or_b32_e32 v10, s8, v35
	v_lshlrev_b32_e32 v10, 12, v10
	v_lshl_add_u64 v[78:79], v[16:17], 0, v[10:11]
	global_load_dword v92, v[78:79], off
	v_or_b32_e32 v10, s8, v37
	v_lshlrev_b32_e32 v10, 12, v10
	v_lshl_add_u64 v[78:79], v[16:17], 0, v[10:11]
	global_load_dword v93, v[78:79], off
	v_or_b32_e32 v10, s8, v39
	v_lshlrev_b32_e32 v10, 12, v10
	v_lshl_add_u64 v[78:79], v[16:17], 0, v[10:11]
	global_load_dword v94, v[78:79], off
	v_or_b32_e32 v10, s8, v41
	v_lshlrev_b32_e32 v10, 12, v10
	v_lshl_add_u64 v[78:79], v[16:17], 0, v[10:11]
	global_load_dword v95, v[78:79], off
	v_or_b32_e32 v10, s8, v43
	v_lshlrev_b32_e32 v10, 12, v10
	v_lshl_add_u64 v[78:79], v[16:17], 0, v[10:11]
	global_load_dword v96, v[78:79], off
	v_or_b32_e32 v10, s8, v45
	v_lshlrev_b32_e32 v10, 12, v10
	v_lshl_add_u64 v[78:79], v[16:17], 0, v[10:11]
	global_load_dword v97, v[78:79], off
	v_or_b32_e32 v10, s8, v47
	v_lshlrev_b32_e32 v10, 12, v10
	v_lshl_add_u64 v[78:79], v[16:17], 0, v[10:11]
	global_load_dword v98, v[78:79], off
	v_or_b32_e32 v10, s8, v49
	v_lshlrev_b32_e32 v10, 12, v10
	v_lshl_add_u64 v[78:79], v[16:17], 0, v[10:11]
	global_load_dword v99, v[78:79], off
	v_or_b32_e32 v10, s8, v51
	v_lshlrev_b32_e32 v10, 12, v10
	v_lshl_add_u64 v[78:79], v[16:17], 0, v[10:11]
	global_load_dword v100, v[78:79], off
	v_or_b32_e32 v10, s8, v61
	v_lshlrev_b32_e32 v10, 12, v10
	v_lshl_add_u64 v[78:79], v[16:17], 0, v[10:11]
	global_load_dword v101, v[78:79], off
	v_or_b32_e32 v10, s8, v62
	v_lshlrev_b32_e32 v10, 12, v10
	v_lshl_add_u64 v[78:79], v[16:17], 0, v[10:11]
	global_load_dword v102, v[78:79], off
	v_or_b32_e32 v10, s8, v63
	v_lshlrev_b32_e32 v10, 12, v10
	v_lshl_add_u64 v[78:79], v[16:17], 0, v[10:11]
	global_load_dword v103, v[78:79], off
	v_or_b32_e32 v10, s8, v64
	v_lshlrev_b32_e32 v10, 12, v10
	v_lshl_add_u64 v[78:79], v[16:17], 0, v[10:11]
	global_load_dword v104, v[78:79], off
	v_or_b32_e32 v10, s8, v65
	v_lshlrev_b32_e32 v10, 12, v10
	v_lshl_add_u64 v[78:79], v[16:17], 0, v[10:11]
	global_load_dword v105, v[78:79], off
	v_or_b32_e32 v10, s8, v66
	v_lshlrev_b32_e32 v10, 12, v10
	v_lshl_add_u64 v[78:79], v[16:17], 0, v[10:11]
	global_load_dword v106, v[78:79], off
	v_or_b32_e32 v10, s8, v67
	v_lshlrev_b32_e32 v10, 12, v10
	v_lshl_add_u64 v[78:79], v[16:17], 0, v[10:11]
	global_load_dword v107, v[78:79], off
	v_or_b32_e32 v10, s8, v68
	v_lshlrev_b32_e32 v10, 12, v10
	v_lshl_add_u64 v[80:81], v[16:17], 0, v[10:11]
	global_load_dword v108, v[80:81], off
	v_or_b32_e32 v10, s8, v69
	v_lshlrev_b32_e32 v10, 12, v10
	v_lshl_add_u64 v[78:79], v[16:17], 0, v[10:11]
	global_load_dword v109, v[78:79], off
	v_or_b32_e32 v10, s8, v70
	v_lshlrev_b32_e32 v10, 12, v10
	v_lshl_add_u64 v[80:81], v[16:17], 0, v[10:11]
	global_load_dword v110, v[80:81], off
	v_or_b32_e32 v10, s8, v71
	v_lshlrev_b32_e32 v10, 12, v10
	v_lshl_add_u64 v[78:79], v[16:17], 0, v[10:11]
	global_load_dword v111, v[78:79], off
	v_or_b32_e32 v10, s8, v72
	v_lshlrev_b32_e32 v10, 12, v10
	v_lshl_add_u64 v[80:81], v[16:17], 0, v[10:11]
	global_load_dword v112, v[80:81], off
	v_or_b32_e32 v10, s8, v73
	v_lshlrev_b32_e32 v10, 12, v10
	v_lshl_add_u64 v[16:17], v[16:17], 0, v[10:11]
	global_load_dword v113, v[16:17], off
	s_waitcnt vmcnt(0)
	v_add_u32_e32 v114, v1, v3
	ds_write_b32 v114, v82
	v_add_lshl_u32 v115, s8, v6, 2
	v_add_u32_e32 v116, v1, v9
	ds_write_b32 v116, v83
	v_add_u32_e32 v117, v1, v20
	ds_write_b32 v117, v84
	v_add_u32_e32 v118, v1, v22
	ds_write_b32 v118, v85
	v_add_u32_e32 v119, v1, v24
	ds_write_b32 v119, v86
	v_add_u32_e32 v120, v1, v26
	ds_write_b32 v120, v87
	v_add_u32_e32 v121, v1, v28
	ds_write_b32 v121, v88
	v_add_u32_e32 v122, v1, v30
	ds_write_b32 v122, v89
	v_add_u32_e32 v123, v1, v32
	ds_write_b32 v123, v90
	v_add_u32_e32 v124, v1, v34
	ds_write_b32 v124, v91
	v_add_u32_e32 v125, v1, v36
	ds_write_b32 v125, v92
	v_add_u32_e32 v126, v1, v38
	ds_write_b32 v126, v93
	v_add_u32_e32 v127, v1, v40
	ds_write_b32 v127, v94
	v_add_u32_e32 v128, v1, v42
	ds_write_b32 v128, v95
	v_add_u32_e32 v129, v1, v44
	ds_write_b32 v129, v96
	v_add_u32_e32 v130, v1, v46
	ds_write_b32 v130, v97
	v_add_u32_e32 v131, v1, v48
	ds_write_b32 v131, v98
	v_add_u32_e32 v132, v1, v50
	ds_write_b32 v132, v99
	v_add_u32_e32 v133, v1, v52
	ds_write_b32 v133, v100
	v_add_u32_e32 v134, v1, v53
	ds_write_b32 v134, v101
	v_add_u32_e32 v135, v1, v54
	ds_write_b32 v135, v102
	v_add_u32_e32 v136, v1, v55
	ds_write_b32 v136, v103
	v_add_u32_e32 v137, v1, v56
	ds_write_b32 v137, v104
	v_add_u32_e32 v138, v1, v57
	ds_write_b32 v138, v105
	v_add_u32_e32 v139, v1, v58
	ds_write_b32 v139, v106
	ds_write_b32 v139, v107 offset:264
	ds_write_b32 v139, v108 offset:528
	ds_write_b32 v139, v109 offset:792
	ds_write_b32 v139, v110 offset:1056
	ds_write_b32 v139, v111 offset:1320
	ds_write_b32 v139, v112 offset:1584
	v_mov_b32_e32 v140, v113
	ds_write_b32 v139, v140 offset:1848

.Lladder_ng_g3:
	global_load_dword v82, v[78:79], off
	v_or_b32_e32 v10, s25, v5
	v_lshlrev_b32_e32 v10, 12, v10
	v_lshl_add_u64 v[78:79], v[16:17], 0, v[10:11]
	global_load_dword v83, v[78:79], off
	v_or_b32_e32 v10, s25, v13
	v_lshlrev_b32_e32 v10, 12, v10
	v_lshl_add_u64 v[78:79], v[16:17], 0, v[10:11]
	global_load_dword v84, v[78:79], off
	v_or_b32_e32 v10, s25, v21
	v_lshlrev_b32_e32 v10, 12, v10
	v_lshl_add_u64 v[78:79], v[16:17], 0, v[10:11]
	global_load_dword v85, v[78:79], off
	v_or_b32_e32 v10, s25, v23
	v_lshlrev_b32_e32 v10, 12, v10
	v_lshl_add_u64 v[78:79], v[16:17], 0, v[10:11]
	global_load_dword v86, v[78:79], off
	v_or_b32_e32 v10, s25, v25
	v_lshlrev_b32_e32 v10, 12, v10
	v_lshl_add_u64 v[78:79], v[16:17], 0, v[10:11]
	global_load_dword v87, v[78:79], off
	v_or_b32_e32 v10, s25, v27
	v_lshlrev_b32_e32 v10, 12, v10
	v_lshl_add_u64 v[78:79], v[16:17], 0, v[10:11]
	global_load_dword v88, v[78:79], off
	v_or_b32_e32 v10, s25, v29
	v_lshlrev_b32_e32 v10, 12, v10
	v_lshl_add_u64 v[78:79], v[16:17], 0, v[10:11]
	global_load_dword v89, v[78:79], off
	v_or_b32_e32 v10, s25, v31
	v_lshlrev_b32_e32 v10, 12, v10
	v_lshl_add_u64 v[78:79], v[16:17], 0, v[10:11]
	global_load_dword v90, v[78:79], off
	v_or_b32_e32 v10, s25, v33
	v_lshlrev_b32_e32 v10, 12, v10
	v_lshl_add_u64 v[78:79], v[16:17], 0, v[10:11]
	global_load_dword v91, v[78:79], off
	v_or_b32_e32 v10, s25, v35
	v_lshlrev_b32_e32 v10, 12, v10
	v_lshl_add_u64 v[78:79], v[16:17], 0, v[10:11]
	global_load_dword v92, v[78:79], off
	v_or_b32_e32 v10, s25, v37
	v_lshlrev_b32_e32 v10, 12, v10
	v_lshl_add_u64 v[78:79], v[16:17], 0, v[10:11]
	global_load_dword v93, v[78:79], off
	v_or_b32_e32 v10, s25, v39
	v_lshlrev_b32_e32 v10, 12, v10
	v_lshl_add_u64 v[78:79], v[16:17], 0, v[10:11]
	global_load_dword v94, v[78:79], off
	v_or_b32_e32 v10, s25, v41
	v_lshlrev_b32_e32 v10, 12, v10
	v_lshl_add_u64 v[78:79], v[16:17], 0, v[10:11]
	global_load_dword v95, v[78:79], off
	v_or_b32_e32 v10, s25, v43
	v_lshlrev_b32_e32 v10, 12, v10
	v_lshl_add_u64 v[78:79], v[16:17], 0, v[10:11]
	global_load_dword v96, v[78:79], off
	v_or_b32_e32 v10, s25, v45
	v_lshlrev_b32_e32 v10, 12, v10
	v_lshl_add_u64 v[78:79], v[16:17], 0, v[10:11]
	global_load_dword v97, v[78:79], off
	v_or_b32_e32 v10, s25, v47
	v_lshlrev_b32_e32 v10, 12, v10
	v_lshl_add_u64 v[78:79], v[16:17], 0, v[10:11]
	global_load_dword v98, v[78:79], off
	v_or_b32_e32 v10, s25, v49
	v_lshlrev_b32_e32 v10, 12, v10
	v_lshl_add_u64 v[78:79], v[16:17], 0, v[10:11]
	global_load_dword v99, v[78:79], off
	v_or_b32_e32 v10, s25, v51
	v_lshlrev_b32_e32 v10, 12, v10
	v_lshl_add_u64 v[78:79], v[16:17], 0, v[10:11]
	global_load_dword v100, v[78:79], off
	v_or_b32_e32 v10, s25, v61
	v_lshlrev_b32_e32 v10, 12, v10
	v_lshl_add_u64 v[78:79], v[16:17], 0, v[10:11]
	global_load_dword v101, v[78:79], off
	v_or_b32_e32 v10, s25, v62
	v_lshlrev_b32_e32 v10, 12, v10
	v_lshl_add_u64 v[78:79], v[16:17], 0, v[10:11]
	global_load_dword v102, v[78:79], off
	v_or_b32_e32 v10, s25, v63
	v_lshlrev_b32_e32 v10, 12, v10
	v_lshl_add_u64 v[78:79], v[16:17], 0, v[10:11]
	global_load_dword v103, v[78:79], off
	v_or_b32_e32 v10, s25, v64
	v_lshlrev_b32_e32 v10, 12, v10
	v_lshl_add_u64 v[78:79], v[16:17], 0, v[10:11]
	global_load_dword v104, v[78:79], off
	v_or_b32_e32 v10, s25, v65
	v_lshlrev_b32_e32 v10, 12, v10
	v_lshl_add_u64 v[78:79], v[16:17], 0, v[10:11]
	global_load_dword v105, v[78:79], off
	v_or_b32_e32 v10, s25, v66
	v_lshlrev_b32_e32 v10, 12, v10
	v_lshl_add_u64 v[78:79], v[16:17], 0, v[10:11]
	global_load_dword v106, v[78:79], off
	v_or_b32_e32 v10, s25, v67
	v_lshlrev_b32_e32 v10, 12, v10
	v_lshl_add_u64 v[78:79], v[16:17], 0, v[10:11]
	global_load_dword v107, v[78:79], off
	v_or_b32_e32 v10, s25, v68
	v_lshlrev_b32_e32 v10, 12, v10
	v_lshl_add_u64 v[80:81], v[16:17], 0, v[10:11]
	global_load_dword v108, v[80:81], off
	v_or_b32_e32 v10, s25, v69
	v_lshlrev_b32_e32 v10, 12, v10
	v_lshl_add_u64 v[78:79], v[16:17], 0, v[10:11]
	global_load_dword v109, v[78:79], off
	v_or_b32_e32 v10, s25, v70
	v_lshlrev_b32_e32 v10, 12, v10
	v_lshl_add_u64 v[80:81], v[16:17], 0, v[10:11]
	global_load_dword v110, v[80:81], off
	v_or_b32_e32 v10, s25, v71
	v_lshlrev_b32_e32 v10, 12, v10
	v_lshl_add_u64 v[78:79], v[16:17], 0, v[10:11]
	global_load_dword v111, v[78:79], off
	v_or_b32_e32 v10, s25, v72
	v_lshlrev_b32_e32 v10, 12, v10
	v_lshl_add_u64 v[80:81], v[16:17], 0, v[10:11]
	global_load_dword v112, v[80:81], off
	v_or_b32_e32 v10, s25, v73
	v_lshlrev_b32_e32 v10, 12, v10
	v_lshl_add_u64 v[16:17], v[16:17], 0, v[10:11]
	global_load_dword v113, v[16:17], off
	s_waitcnt vmcnt(0)
	v_add_u32_e32 v114, v1, v3
	ds_write_b32 v114, v82
	v_add_lshl_u32 v115, s25, v6, 2
	v_add_u32_e32 v116, v1, v9
	ds_write_b32 v116, v83
	v_add_u32_e32 v117, v1, v20
	ds_write_b32 v117, v84
	v_add_u32_e32 v118, v1, v22
	ds_write_b32 v118, v85
	v_add_u32_e32 v119, v1, v24
	ds_write_b32 v119, v86
	v_add_u32_e32 v120, v1, v26
	ds_write_b32 v120, v87
	v_add_u32_e32 v121, v1, v28
	ds_write_b32 v121, v88
	v_add_u32_e32 v122, v1, v30
	ds_write_b32 v122, v89
	v_add_u32_e32 v123, v1, v32
	ds_write_b32 v123, v90
	v_add_u32_e32 v124, v1, v34
	ds_write_b32 v124, v91
	v_add_u32_e32 v125, v1, v36
	ds_write_b32 v125, v92
	v_add_u32_e32 v126, v1, v38
	ds_write_b32 v126, v93
	v_add_u32_e32 v127, v1, v40
	ds_write_b32 v127, v94
	v_add_u32_e32 v128, v1, v42
	ds_write_b32 v128, v95
	v_add_u32_e32 v129, v1, v44
	ds_write_b32 v129, v96
	v_add_u32_e32 v130, v1, v46
	ds_write_b32 v130, v97
	v_add_u32_e32 v131, v1, v48
	ds_write_b32 v131, v98
	v_add_u32_e32 v132, v1, v50
	ds_write_b32 v132, v99
	v_add_u32_e32 v133, v1, v52
	ds_write_b32 v133, v100
	v_add_u32_e32 v134, v1, v53
	ds_write_b32 v134, v101
	v_add_u32_e32 v135, v1, v54
	ds_write_b32 v135, v102
	v_add_u32_e32 v136, v1, v55
	ds_write_b32 v136, v103
	v_add_u32_e32 v137, v1, v56
	ds_write_b32 v137, v104
	v_add_u32_e32 v138, v1, v57
	ds_write_b32 v138, v105
	v_add_u32_e32 v139, v1, v58
	ds_write_b32 v139, v106
	ds_write_b32 v139, v107 offset:264
	ds_write_b32 v139, v108 offset:528
	ds_write_b32 v139, v109 offset:792
	ds_write_b32 v139, v110 offset:1056
	ds_write_b32 v139, v111 offset:1320
	ds_write_b32 v139, v112 offset:1584
	v_mov_b32_e32 v140, v113
	ds_write_b32 v139, v140 offset:1848

.LBB0_305:
	s_add_u32 s22, s40, s28
	s_addc_u32 s23, s41, 0
	s_load_dwordx4 s[4:7], s[22:23], 0x40
	s_and_b64 s[22:23], s[20:21], exec
	s_cselect_b32 s8, 0x800000, 0
	v_lshlrev_b32_e32 v10, 2, v8
	s_waitcnt lgkmcnt(0)
	s_add_u32 s8, s6, s8
	s_addc_u32 s38, s7, 0
	s_and_b64 s[6:7], s[20:21], exec
	s_cselect_b32 s6, 0x1000, 0
	s_add_u32 s22, s4, s6
	s_addc_u32 s23, s5, 0
	s_ashr_i32 s6, s24, 31
	s_lshr_b32 s6, s6, 26
	s_add_i32 s6, s24, s6
	s_and_b32 s20, s6, 0xffffffc0
	s_sub_i32 s6, s24, s20
	s_lshl_b32 s6, s6, 5
	s_ashr_i32 s7, s6, 31
	s_lshl_b64 s[24:25], s[6:7], 2
	s_add_u32 s24, s8, s24
	v_or_b32_e32 v18, s20, v6
	s_addc_u32 s25, s38, s25
	v_ashrrev_i32_e32 v19, 31, v18
	v_lshl_add_u64 v[16:17], s[24:25], 0, v[10:11]
	v_lshlrev_b64 v[78:79], 13, v[18:19]
	v_lshl_add_u64 v[78:79], v[16:17], 0, v[78:79]
	s_cmp_eq_u64 s[4:5], 0
	s_cbranch_scc1 .Lladder_ng_g4
	global_load_dword v80, v[78:79], off
	v_lshl_add_u64 v[18:19], v[18:19], 2, s[22:23]
	global_load_dword v81, v[18:19], off
	v_or_b32_e32 v18, s20, v5
	v_ashrrev_i32_e32 v19, 31, v18
	v_lshlrev_b64 v[18:19], 13, v[18:19]
	v_lshl_add_u64 v[18:19], v[16:17], 0, v[18:19]
	global_load_dword v82, v[18:19], off
	s_ashr_i32 s21, s20, 31
	v_lshl_add_u64 v[18:19], s[20:21], 0, v[6:7]
	v_lshl_add_u64 v[18:19], v[18:19], 2, s[22:23]
	global_load_dword v83, v[18:19], off offset:8
	v_or_b32_e32 v18, s20, v13
	v_ashrrev_i32_e32 v19, 31, v18
	v_lshlrev_b64 v[18:19], 13, v[18:19]
	v_lshl_add_u64 v[18:19], v[16:17], 0, v[18:19]
	global_load_dword v84, v[18:19], off
	s_ashr_i32 s21, s20, 31
	v_lshl_add_u64 v[78:79], s[20:21], 0, v[6:7]
	v_lshl_add_u64 v[78:79], v[78:79], 2, s[22:23]
	global_load_dword v85, v[78:79], off offset:16
	v_or_b32_e32 v78, s20, v21
	v_ashrrev_i32_e32 v79, 31, v78
	v_lshlrev_b64 v[78:79], 13, v[78:79]
	v_lshl_add_u64 v[78:79], v[16:17], 0, v[78:79]
	global_load_dword v86, v[78:79], off
	s_ashr_i32 s21, s20, 31
	v_lshl_add_u64 v[18:19], s[20:21], 0, v[6:7]
	v_lshl_add_u64 v[18:19], v[18:19], 2, s[22:23]
	global_load_dword v87, v[18:19], off offset:24
	v_or_b32_e32 v18, s20, v23
	v_ashrrev_i32_e32 v19, 31, v18
	v_lshlrev_b64 v[18:19], 13, v[18:19]
	v_lshl_add_u64 v[18:19], v[16:17], 0, v[18:19]
	global_load_dword v88, v[18:19], off
	s_ashr_i32 s21, s20, 31
	v_lshl_add_u64 v[78:79], s[20:21], 0, v[6:7]
	v_lshl_add_u64 v[78:79], v[78:79], 2, s[22:23]
	global_load_dword v89, v[78:79], off offset:32
	v_or_b32_e32 v78, s20, v25
	v_ashrrev_i32_e32 v79, 31, v78
	v_lshlrev_b64 v[78:79], 13, v[78:79]
	v_lshl_add_u64 v[78:79], v[16:17], 0, v[78:79]
	global_load_dword v90, v[78:79], off
	s_ashr_i32 s21, s20, 31
	v_lshl_add_u64 v[18:19], s[20:21], 0, v[6:7]
	v_lshl_add_u64 v[18:19], v[18:19], 2, s[22:23]
	global_load_dword v91, v[18:19], off offset:40
	v_or_b32_e32 v18, s20, v27
	v_ashrrev_i32_e32 v19, 31, v18
	v_lshlrev_b64 v[18:19], 13, v[18:19]
	v_lshl_add_u64 v[18:19], v[16:17], 0, v[18:19]
	global_load_dword v92, v[18:19], off
	s_ashr_i32 s21, s20, 31
	v_lshl_add_u64 v[78:79], s[20:21], 0, v[6:7]
	v_lshl_add_u64 v[78:79], v[78:79], 2, s[22:23]
	global_load_dword v93, v[78:79], off offset:48
	v_or_b32_e32 v78, s20, v29
	v_ashrrev_i32_e32 v79, 31, v78
	v_lshlrev_b64 v[78:79], 13, v[78:79]
	v_lshl_add_u64 v[78:79], v[16:17], 0, v[78:79]
	global_load_dword v94, v[78:79], off
	s_ashr_i32 s21, s20, 31
	v_lshl_add_u64 v[18:19], s[20:21], 0, v[6:7]
	v_lshl_add_u64 v[18:19], v[18:19], 2, s[22:23]
	global_load_dword v95, v[18:19], off offset:56
	v_or_b32_e32 v18, s20, v31
	v_ashrrev_i32_e32 v19, 31, v18
	v_lshlrev_b64 v[18:19], 13, v[18:19]
	v_lshl_add_u64 v[18:19], v[16:17], 0, v[18:19]
	global_load_dword v96, v[18:19], off
	s_ashr_i32 s21, s20, 31
	v_lshl_add_u64 v[78:79], s[20:21], 0, v[6:7]
	v_lshl_add_u64 v[78:79], v[78:79], 2, s[22:23]
	global_load_dword v97, v[78:79], off offset:64
	v_or_b32_e32 v78, s20, v33
	v_ashrrev_i32_e32 v79, 31, v78
	v_lshlrev_b64 v[78:79], 13, v[78:79]
	v_lshl_add_u64 v[78:79], v[16:17], 0, v[78:79]
	global_load_dword v98, v[78:79], off
	s_ashr_i32 s21, s20, 31
	v_lshl_add_u64 v[18:19], s[20:21], 0, v[6:7]
	v_lshl_add_u64 v[18:19], v[18:19], 2, s[22:23]
	global_load_dword v99, v[18:19], off offset:72
	v_or_b32_e32 v18, s20, v35
	v_ashrrev_i32_e32 v19, 31, v18
	v_lshlrev_b64 v[18:19], 13, v[18:19]
	v_lshl_add_u64 v[18:19], v[16:17], 0, v[18:19]
	global_load_dword v100, v[18:19], off
	s_ashr_i32 s21, s20, 31
	v_lshl_add_u64 v[78:79], s[20:21], 0, v[6:7]
	v_lshl_add_u64 v[78:79], v[78:79], 2, s[22:23]
	global_load_dword v101, v[78:79], off offset:80
	v_or_b32_e32 v78, s20, v37
	v_ashrrev_i32_e32 v79, 31, v78
	v_lshlrev_b64 v[78:79], 13, v[78:79]
	v_lshl_add_u64 v[78:79], v[16:17], 0, v[78:79]
	global_load_dword v102, v[78:79], off
	s_ashr_i32 s21, s20, 31
	v_lshl_add_u64 v[18:19], s[20:21], 0, v[6:7]
	v_lshl_add_u64 v[18:19], v[18:19], 2, s[22:23]
	global_load_dword v103, v[18:19], off offset:88
	v_or_b32_e32 v18, s20, v39
	v_ashrrev_i32_e32 v19, 31, v18
	v_lshlrev_b64 v[18:19], 13, v[18:19]
	v_lshl_add_u64 v[18:19], v[16:17], 0, v[18:19]
	global_load_dword v104, v[18:19], off
	s_ashr_i32 s21, s20, 31
	v_lshl_add_u64 v[78:79], s[20:21], 0, v[6:7]
	v_lshl_add_u64 v[78:79], v[78:79], 2, s[22:23]
	global_load_dword v105, v[78:79], off offset:96
	v_or_b32_e32 v78, s20, v41
	v_ashrrev_i32_e32 v79, 31, v78
	v_lshlrev_b64 v[78:79], 13, v[78:79]
	v_lshl_add_u64 v[78:79], v[16:17], 0, v[78:79]
	global_load_dword v106, v[78:79], off
	s_ashr_i32 s21, s20, 31
	v_lshl_add_u64 v[18:19], s[20:21], 0, v[6:7]
	v_lshl_add_u64 v[18:19], v[18:19], 2, s[22:23]
	global_load_dword v107, v[18:19], off offset:104
	v_or_b32_e32 v18, s20, v43
	v_ashrrev_i32_e32 v19, 31, v18
	v_lshlrev_b64 v[18:19], 13, v[18:19]
	v_lshl_add_u64 v[18:19], v[16:17], 0, v[18:19]
	global_load_dword v108, v[18:19], off
	s_ashr_i32 s21, s20, 31
	v_lshl_add_u64 v[78:79], s[20:21], 0, v[6:7]
	v_lshl_add_u64 v[78:79], v[78:79], 2, s[22:23]
	global_load_dword v109, v[78:79], off offset:112
	v_or_b32_e32 v78, s20, v45
	v_ashrrev_i32_e32 v79, 31, v78
	v_lshlrev_b64 v[78:79], 13, v[78:79]
	v_lshl_add_u64 v[78:79], v[16:17], 0, v[78:79]
	global_load_dword v110, v[78:79], off
	s_ashr_i32 s21, s20, 31
	v_lshl_add_u64 v[18:19], s[20:21], 0, v[6:7]
	v_lshl_add_u64 v[18:19], v[18:19], 2, s[22:23]
	global_load_dword v111, v[18:19], off offset:120
	v_or_b32_e32 v18, s20, v47
	v_ashrrev_i32_e32 v19, 31, v18
	v_lshlrev_b64 v[18:19], 13, v[18:19]
	v_lshl_add_u64 v[18:19], v[16:17], 0, v[18:19]
	global_load_dword v112, v[18:19], off
	s_ashr_i32 s21, s20, 31
	v_lshl_add_u64 v[78:79], s[20:21], 0, v[6:7]
	v_lshl_add_u64 v[78:79], v[78:79], 2, s[22:23]
	global_load_dword v113, v[78:79], off offset:128
	v_or_b32_e32 v78, s20, v49
	v_ashrrev_i32_e32 v79, 31, v78
	v_lshlrev_b64 v[78:79], 13, v[78:79]
	v_lshl_add_u64 v[78:79], v[16:17], 0, v[78:79]
	global_load_dword v114, v[78:79], off
	s_ashr_i32 s21, s20, 31
	v_lshl_add_u64 v[18:19], s[20:21], 0, v[6:7]
	v_lshl_add_u64 v[18:19], v[18:19], 2, s[22:23]
	global_load_dword v115, v[18:19], off offset:136
	v_or_b32_e32 v18, s20, v51
	v_ashrrev_i32_e32 v19, 31, v18
	v_lshlrev_b64 v[18:19], 13, v[18:19]
	v_lshl_add_u64 v[18:19], v[16:17], 0, v[18:19]
	global_load_dword v116, v[18:19], off
	s_ashr_i32 s21, s20, 31
	v_lshl_add_u64 v[78:79], s[20:21], 0, v[6:7]
	v_lshl_add_u64 v[78:79], v[78:79], 2, s[22:23]
	global_load_dword v117, v[78:79], off offset:144
	v_or_b32_e32 v78, s20, v61
	v_ashrrev_i32_e32 v79, 31, v78
	v_lshlrev_b64 v[78:79], 13, v[78:79]
	v_lshl_add_u64 v[78:79], v[16:17], 0, v[78:79]
	global_load_dword v118, v[78:79], off
	s_ashr_i32 s21, s20, 31
	v_lshl_add_u64 v[18:19], s[20:21], 0, v[6:7]
	v_lshl_add_u64 v[18:19], v[18:19], 2, s[22:23]
	global_load_dword v119, v[18:19], off offset:152
	v_or_b32_e32 v18, s20, v62
	v_ashrrev_i32_e32 v19, 31, v18
	v_lshlrev_b64 v[18:19], 13, v[18:19]
	v_lshl_add_u64 v[18:19], v[16:17], 0, v[18:19]
	global_load_dword v120, v[18:19], off
	s_ashr_i32 s21, s20, 31
	v_lshl_add_u64 v[78:79], s[20:21], 0, v[6:7]
	v_lshl_add_u64 v[78:79], v[78:79], 2, s[22:23]
	global_load_dword v121, v[78:79], off offset:160
	v_or_b32_e32 v78, s20, v63
	v_ashrrev_i32_e32 v79, 31, v78
	v_lshlrev_b64 v[78:79], 13, v[78:79]
	v_lshl_add_u64 v[78:79], v[16:17], 0, v[78:79]
	global_load_dword v122, v[78:79], off
	s_ashr_i32 s21, s20, 31
	v_lshl_add_u64 v[18:19], s[20:21], 0, v[6:7]
	v_lshl_add_u64 v[18:19], v[18:19], 2, s[22:23]
	global_load_dword v123, v[18:19], off offset:168
	v_or_b32_e32 v18, s20, v64
	v_ashrrev_i32_e32 v19, 31, v18
	v_lshlrev_b64 v[18:19], 13, v[18:19]
	v_lshl_add_u64 v[18:19], v[16:17], 0, v[18:19]
	global_load_dword v124, v[18:19], off
	s_ashr_i32 s21, s20, 31
	v_lshl_add_u64 v[78:79], s[20:21], 0, v[6:7]
	v_lshl_add_u64 v[78:79], v[78:79], 2, s[22:23]
	global_load_dword v125, v[78:79], off offset:176
	v_or_b32_e32 v78, s20, v65
	v_ashrrev_i32_e32 v79, 31, v78
	v_lshlrev_b64 v[78:79], 13, v[78:79]
	v_lshl_add_u64 v[78:79], v[16:17], 0, v[78:79]
	global_load_dword v126, v[78:79], off
	s_ashr_i32 s21, s20, 31
	v_lshl_add_u64 v[18:19], s[20:21], 0, v[6:7]
	v_lshl_add_u64 v[18:19], v[18:19], 2, s[22:23]
	global_load_dword v127, v[18:19], off offset:184
	v_or_b32_e32 v18, s20, v66
	v_ashrrev_i32_e32 v19, 31, v18
	v_lshlrev_b64 v[18:19], 13, v[18:19]
	v_lshl_add_u64 v[18:19], v[16:17], 0, v[18:19]
	global_load_dword v128, v[18:19], off
	s_ashr_i32 s21, s20, 31
	v_lshl_add_u64 v[78:79], s[20:21], 0, v[6:7]
	v_lshl_add_u64 v[78:79], v[78:79], 2, s[22:23]
	global_load_dword v129, v[78:79], off offset:192
	v_or_b32_e32 v78, s20, v67
	v_ashrrev_i32_e32 v79, 31, v78
	v_lshlrev_b64 v[78:79], 13, v[78:79]
	v_lshl_add_u64 v[78:79], v[16:17], 0, v[78:79]
	global_load_dword v130, v[78:79], off
	s_ashr_i32 s21, s20, 31
	v_lshl_add_u64 v[78:79], s[20:21], 0, v[6:7]
	v_lshl_add_u64 v[78:79], v[78:79], 2, s[22:23]
	global_load_dword v131, v[78:79], off offset:200
	v_or_b32_e32 v78, s20, v68
	v_ashrrev_i32_e32 v79, 31, v78
	v_lshlrev_b64 v[78:79], 13, v[78:79]
	v_lshl_add_u64 v[78:79], v[16:17], 0, v[78:79]
	global_load_dword v132, v[78:79], off
	s_ashr_i32 s21, s20, 31
	v_lshl_add_u64 v[78:79], s[20:21], 0, v[6:7]
	v_lshl_add_u64 v[78:79], v[78:79], 2, s[22:23]
	global_load_dword v133, v[78:79], off offset:208
	v_or_b32_e32 v78, s20, v69
	v_ashrrev_i32_e32 v79, 31, v78
	v_lshlrev_b64 v[78:79], 13, v[78:79]
	v_lshl_add_u64 v[78:79], v[16:17], 0, v[78:79]
	global_load_dword v134, v[78:79], off
	s_ashr_i32 s21, s20, 31
	v_lshl_add_u64 v[78:79], s[20:21], 0, v[6:7]
	v_lshl_add_u64 v[78:79], v[78:79], 2, s[22:23]
	global_load_dword v135, v[78:79], off offset:216
	v_or_b32_e32 v78, s20, v70
	v_ashrrev_i32_e32 v79, 31, v78
	v_lshlrev_b64 v[78:79], 13, v[78:79]
	v_lshl_add_u64 v[78:79], v[16:17], 0, v[78:79]
	global_load_dword v136, v[78:79], off
	s_ashr_i32 s21, s20, 31
	v_lshl_add_u64 v[78:79], s[20:21], 0, v[6:7]
	v_lshl_add_u64 v[78:79], v[78:79], 2, s[22:23]
	global_load_dword v137, v[78:79], off offset:224
	v_or_b32_e32 v78, s20, v71
	v_ashrrev_i32_e32 v79, 31, v78
	v_lshlrev_b64 v[78:79], 13, v[78:79]
	v_lshl_add_u64 v[78:79], v[16:17], 0, v[78:79]
	global_load_dword v138, v[78:79], off
	s_ashr_i32 s21, s20, 31
	v_lshl_add_u64 v[78:79], s[20:21], 0, v[6:7]
	v_lshl_add_u64 v[78:79], v[78:79], 2, s[22:23]
	global_load_dword v139, v[78:79], off offset:232
	v_or_b32_e32 v78, s20, v72
	v_ashrrev_i32_e32 v79, 31, v78
	v_lshlrev_b64 v[78:79], 13, v[78:79]
	v_lshl_add_u64 v[78:79], v[16:17], 0, v[78:79]
	global_load_dword v140, v[78:79], off
	s_ashr_i32 s21, s20, 31
	v_lshl_add_u64 v[78:79], s[20:21], 0, v[6:7]
	v_lshl_add_u64 v[78:79], v[78:79], 2, s[22:23]
	global_load_dword v141, v[78:79], off offset:240
	v_or_b32_e32 v78, s20, v73
	v_ashrrev_i32_e32 v79, 31, v78
	v_lshlrev_b64 v[78:79], 13, v[78:79]
	v_lshl_add_u64 v[16:17], v[16:17], 0, v[78:79]
	global_load_dword v142, v[16:17], off
	s_ashr_i32 s21, s20, 31
	v_lshl_add_u64 v[18:19], s[20:21], 0, v[6:7]
	v_lshl_add_u64 v[18:19], v[18:19], 2, s[22:23]
	global_load_dword v143, v[18:19], off offset:248
	s_waitcnt vmcnt(0)
	v_mul_f32_e32 v80, v80, v81
	v_add_u32_e32 v144, v1, v3
	ds_write_b32 v144, v80
	v_mul_f32_e32 v82, v82, v83
	v_add_u32_e32 v145, v1, v9
	ds_write_b32 v145, v82
	v_mul_f32_e32 v84, v84, v85
	v_add_u32_e32 v146, v1, v20
	ds_write_b32 v146, v84
	v_mul_f32_e32 v86, v86, v87
	v_add_u32_e32 v147, v1, v22
	ds_write_b32 v147, v86
	v_mul_f32_e32 v88, v88, v89
	v_add_u32_e32 v148, v1, v24
	ds_write_b32 v148, v88
	v_mul_f32_e32 v90, v90, v91
	v_add_u32_e32 v149, v1, v26
	ds_write_b32 v149, v90
	v_mul_f32_e32 v92, v92, v93
	v_add_u32_e32 v150, v1, v28
	ds_write_b32 v150, v92
	v_mul_f32_e32 v94, v94, v95
	v_add_u32_e32 v151, v1, v30
	ds_write_b32 v151, v94
	v_mul_f32_e32 v96, v96, v97
	v_add_u32_e32 v152, v1, v32
	ds_write_b32 v152, v96
	v_mul_f32_e32 v98, v98, v99
	v_add_u32_e32 v153, v1, v34
	ds_write_b32 v153, v98
	v_mul_f32_e32 v100, v100, v101
	v_add_u32_e32 v154, v1, v36
	ds_write_b32 v154, v100
	v_mul_f32_e32 v102, v102, v103
	v_add_u32_e32 v155, v1, v38
	ds_write_b32 v155, v102
	v_mul_f32_e32 v104, v104, v105
	v_add_u32_e32 v156, v1, v40
	ds_write_b32 v156, v104
	v_mul_f32_e32 v106, v106, v107
	v_add_u32_e32 v157, v1, v42
	ds_write_b32 v157, v106
	v_mul_f32_e32 v108, v108, v109
	v_add_u32_e32 v158, v1, v44
	ds_write_b32 v158, v108
	v_mul_f32_e32 v110, v110, v111
	v_add_u32_e32 v159, v1, v46
	ds_write_b32 v159, v110
	v_mul_f32_e32 v112, v112, v113
	v_add_u32_e32 v160, v1, v48
	ds_write_b32 v160, v112
	v_mul_f32_e32 v114, v114, v115
	v_add_u32_e32 v161, v1, v50
	ds_write_b32 v161, v114
	v_mul_f32_e32 v116, v116, v117
	v_add_u32_e32 v162, v1, v52
	ds_write_b32 v162, v116
	v_mul_f32_e32 v118, v118, v119
	v_add_u32_e32 v163, v1, v53
	ds_write_b32 v163, v118
	v_mul_f32_e32 v120, v120, v121
	v_add_u32_e32 v164, v1, v54
	ds_write_b32 v164, v120
	v_mul_f32_e32 v122, v122, v123
	v_add_u32_e32 v165, v1, v55
	ds_write_b32 v165, v122
	v_mul_f32_e32 v124, v124, v125
	v_add_u32_e32 v166, v1, v56
	ds_write_b32 v166, v124
	v_mul_f32_e32 v126, v126, v127
	v_add_u32_e32 v167, v1, v57
	ds_write_b32 v167, v126
	v_mul_f32_e32 v128, v128, v129
	v_add_u32_e32 v168, v1, v58
	ds_write_b32 v168, v128
	v_mul_f32_e32 v130, v130, v131
	ds_write_b32 v168, v130 offset:264
	v_mul_f32_e32 v132, v132, v133
	ds_write_b32 v168, v132 offset:528
	v_mul_f32_e32 v134, v134, v135
	ds_write_b32 v168, v134 offset:792
	v_mul_f32_e32 v136, v136, v137
	ds_write_b32 v168, v136 offset:1056
	v_mul_f32_e32 v138, v138, v139
	ds_write_b32 v168, v138 offset:1320
	v_mul_f32_e32 v140, v140, v141
	ds_write_b32 v168, v140 offset:1584
	v_mul_f32_e32 v143, v142, v143
	v_mov_b32_e32 v10, v168
	v_mov_b32_e32 v17, v143
	s_branch .LBB0_16
.Lladder_ng_g4:
	global_load_dword v80, v[78:79], off
	v_or_b32_e32 v18, s20, v5
	v_ashrrev_i32_e32 v19, 31, v18
	v_lshlrev_b64 v[18:19], 13, v[18:19]
	v_lshl_add_u64 v[18:19], v[16:17], 0, v[18:19]
	global_load_dword v81, v[18:19], off
	v_or_b32_e32 v18, s20, v13
	v_ashrrev_i32_e32 v19, 31, v18
	v_lshlrev_b64 v[18:19], 13, v[18:19]
	v_lshl_add_u64 v[18:19], v[16:17], 0, v[18:19]
	global_load_dword v82, v[18:19], off
	v_or_b32_e32 v78, s20, v21
	v_ashrrev_i32_e32 v79, 31, v78
	v_lshlrev_b64 v[78:79], 13, v[78:79]
	v_lshl_add_u64 v[78:79], v[16:17], 0, v[78:79]
	global_load_dword v83, v[78:79], off
	v_or_b32_e32 v18, s20, v23
	v_ashrrev_i32_e32 v19, 31, v18
	v_lshlrev_b64 v[18:19], 13, v[18:19]
	v_lshl_add_u64 v[18:19], v[16:17], 0, v[18:19]
	global_load_dword v84, v[18:19], off
	v_or_b32_e32 v78, s20, v25
	v_ashrrev_i32_e32 v79, 31, v78
	v_lshlrev_b64 v[78:79], 13, v[78:79]
	v_lshl_add_u64 v[78:79], v[16:17], 0, v[78:79]
	global_load_dword v85, v[78:79], off
	v_or_b32_e32 v18, s20, v27
	v_ashrrev_i32_e32 v19, 31, v18
	v_lshlrev_b64 v[18:19], 13, v[18:19]
	v_lshl_add_u64 v[18:19], v[16:17], 0, v[18:19]
	global_load_dword v86, v[18:19], off
	v_or_b32_e32 v78, s20, v29
	v_ashrrev_i32_e32 v79, 31, v78
	v_lshlrev_b64 v[78:79], 13, v[78:79]
	v_lshl_add_u64 v[78:79], v[16:17], 0, v[78:79]
	global_load_dword v87, v[78:79], off
	v_or_b32_e32 v18, s20, v31
	v_ashrrev_i32_e32 v19, 31, v18
	v_lshlrev_b64 v[18:19], 13, v[18:19]
	v_lshl_add_u64 v[18:19], v[16:17], 0, v[18:19]
	global_load_dword v88, v[18:19], off
	v_or_b32_e32 v78, s20, v33
	v_ashrrev_i32_e32 v79, 31, v78
	v_lshlrev_b64 v[78:79], 13, v[78:79]
	v_lshl_add_u64 v[78:79], v[16:17], 0, v[78:79]
	global_load_dword v89, v[78:79], off
	v_or_b32_e32 v18, s20, v35
	v_ashrrev_i32_e32 v19, 31, v18
	v_lshlrev_b64 v[18:19], 13, v[18:19]
	v_lshl_add_u64 v[18:19], v[16:17], 0, v[18:19]
	global_load_dword v90, v[18:19], off
	v_or_b32_e32 v78, s20, v37
	v_ashrrev_i32_e32 v79, 31, v78
	v_lshlrev_b64 v[78:79], 13, v[78:79]
	v_lshl_add_u64 v[78:79], v[16:17], 0, v[78:79]
	global_load_dword v91, v[78:79], off
	v_or_b32_e32 v18, s20, v39
	v_ashrrev_i32_e32 v19, 31, v18
	v_lshlrev_b64 v[18:19], 13, v[18:19]
	v_lshl_add_u64 v[18:19], v[16:17], 0, v[18:19]
	global_load_dword v92, v[18:19], off
	v_or_b32_e32 v78, s20, v41
	v_ashrrev_i32_e32 v79, 31, v78
	v_lshlrev_b64 v[78:79], 13, v[78:79]
	v_lshl_add_u64 v[78:79], v[16:17], 0, v[78:79]
	global_load_dword v93, v[78:79], off
	v_or_b32_e32 v18, s20, v43
	v_ashrrev_i32_e32 v19, 31, v18
	v_lshlrev_b64 v[18:19], 13, v[18:19]
	v_lshl_add_u64 v[18:19], v[16:17], 0, v[18:19]
	global_load_dword v94, v[18:19], off
	v_or_b32_e32 v78, s20, v45
	v_ashrrev_i32_e32 v79, 31, v78
	v_lshlrev_b64 v[78:79], 13, v[78:79]
	v_lshl_add_u64 v[78:79], v[16:17], 0, v[78:79]
	global_load_dword v95, v[78:79], off
	v_or_b32_e32 v18, s20, v47
	v_ashrrev_i32_e32 v19, 31, v18
	v_lshlrev_b64 v[18:19], 13, v[18:19]
	v_lshl_add_u64 v[18:19], v[16:17], 0, v[18:19]
	global_load_dword v96, v[18:19], off
	v_or_b32_e32 v78, s20, v49
	v_ashrrev_i32_e32 v79, 31, v78
	v_lshlrev_b64 v[78:79], 13, v[78:79]
	v_lshl_add_u64 v[78:79], v[16:17], 0, v[78:79]
	global_load_dword v97, v[78:79], off
	v_or_b32_e32 v18, s20, v51
	v_ashrrev_i32_e32 v19, 31, v18
	v_lshlrev_b64 v[18:19], 13, v[18:19]
	v_lshl_add_u64 v[18:19], v[16:17], 0, v[18:19]
	global_load_dword v98, v[18:19], off
	v_or_b32_e32 v78, s20, v61
	v_ashrrev_i32_e32 v79, 31, v78
	v_lshlrev_b64 v[78:79], 13, v[78:79]
	v_lshl_add_u64 v[78:79], v[16:17], 0, v[78:79]
	global_load_dword v99, v[78:79], off
	v_or_b32_e32 v18, s20, v62
	v_ashrrev_i32_e32 v19, 31, v18
	v_lshlrev_b64 v[18:19], 13, v[18:19]
	v_lshl_add_u64 v[18:19], v[16:17], 0, v[18:19]
	global_load_dword v100, v[18:19], off
	v_or_b32_e32 v78, s20, v63
	v_ashrrev_i32_e32 v79, 31, v78
	v_lshlrev_b64 v[78:79], 13, v[78:79]
	v_lshl_add_u64 v[78:79], v[16:17], 0, v[78:79]
	global_load_dword v101, v[78:79], off
	v_or_b32_e32 v18, s20, v64
	v_ashrrev_i32_e32 v19, 31, v18
	v_lshlrev_b64 v[18:19], 13, v[18:19]
	v_lshl_add_u64 v[18:19], v[16:17], 0, v[18:19]
	global_load_dword v102, v[18:19], off
	v_or_b32_e32 v78, s20, v65
	v_ashrrev_i32_e32 v79, 31, v78
	v_lshlrev_b64 v[78:79], 13, v[78:79]
	v_lshl_add_u64 v[78:79], v[16:17], 0, v[78:79]
	global_load_dword v103, v[78:79], off
	v_or_b32_e32 v18, s20, v66
	v_ashrrev_i32_e32 v19, 31, v18
	v_lshlrev_b64 v[18:19], 13, v[18:19]
	v_lshl_add_u64 v[18:19], v[16:17], 0, v[18:19]
	global_load_dword v104, v[18:19], off
	v_or_b32_e32 v78, s20, v67
	v_ashrrev_i32_e32 v79, 31, v78
	v_lshlrev_b64 v[78:79], 13, v[78:79]
	v_lshl_add_u64 v[78:79], v[16:17], 0, v[78:79]
	global_load_dword v105, v[78:79], off
	v_or_b32_e32 v78, s20, v68
	v_ashrrev_i32_e32 v79, 31, v78
	v_lshlrev_b64 v[78:79], 13, v[78:79]
	v_lshl_add_u64 v[78:79], v[16:17], 0, v[78:79]
	global_load_dword v106, v[78:79], off
	v_or_b32_e32 v78, s20, v69
	v_ashrrev_i32_e32 v79, 31, v78
	v_lshlrev_b64 v[78:79], 13, v[78:79]
	v_lshl_add_u64 v[78:79], v[16:17], 0, v[78:79]
	global_load_dword v107, v[78:79], off
	v_or_b32_e32 v78, s20, v70
	v_ashrrev_i32_e32 v79, 31, v78
	v_lshlrev_b64 v[78:79], 13, v[78:79]
	v_lshl_add_u64 v[78:79], v[16:17], 0, v[78:79]
	global_load_dword v108, v[78:79], off
	v_or_b32_e32 v78, s20, v71
	v_ashrrev_i32_e32 v79, 31, v78
	v_lshlrev_b64 v[78:79], 13, v[78:79]
	v_lshl_add_u64 v[78:79], v[16:17], 0, v[78:79]
	global_load_dword v109, v[78:79], off
	v_or_b32_e32 v78, s20, v72
	v_ashrrev_i32_e32 v79, 31, v78
	v_lshlrev_b64 v[78:79], 13, v[78:79]
	v_lshl_add_u64 v[78:79], v[16:17], 0, v[78:79]
	global_load_dword v110, v[78:79], off
	v_or_b32_e32 v78, s20, v73
	v_ashrrev_i32_e32 v79, 31, v78
	v_lshlrev_b64 v[78:79], 13, v[78:79]
	v_lshl_add_u64 v[16:17], v[16:17], 0, v[78:79]
	global_load_dword v111, v[16:17], off
	s_waitcnt vmcnt(0)
	v_add_u32_e32 v112, v1, v3
	ds_write_b32 v112, v80
	v_add_u32_e32 v113, v1, v9
	ds_write_b32 v113, v81
	v_add_u32_e32 v114, v1, v20
	ds_write_b32 v114, v82
	v_add_u32_e32 v115, v1, v22
	ds_write_b32 v115, v83
	v_add_u32_e32 v116, v1, v24
	ds_write_b32 v116, v84
	v_add_u32_e32 v117, v1, v26
	ds_write_b32 v117, v85
	v_add_u32_e32 v118, v1, v28
	ds_write_b32 v118, v86
	v_add_u32_e32 v119, v1, v30
	ds_write_b32 v119, v87
	v_add_u32_e32 v120, v1, v32
	ds_write_b32 v120, v88
	v_add_u32_e32 v121, v1, v34
	ds_write_b32 v121, v89
	v_add_u32_e32 v122, v1, v36
	ds_write_b32 v122, v90
	v_add_u32_e32 v123, v1, v38
	ds_write_b32 v123, v91
	v_add_u32_e32 v124, v1, v40
	ds_write_b32 v124, v92
	v_add_u32_e32 v125, v1, v42
	ds_write_b32 v125, v93
	v_add_u32_e32 v126, v1, v44
	ds_write_b32 v126, v94
	v_add_u32_e32 v127, v1, v46
	ds_write_b32 v127, v95
	v_add_u32_e32 v128, v1, v48
	ds_write_b32 v128, v96
	v_add_u32_e32 v129, v1, v50
	ds_write_b32 v129, v97
	v_add_u32_e32 v130, v1, v52
	ds_write_b32 v130, v98
	v_add_u32_e32 v131, v1, v53
	ds_write_b32 v131, v99
	v_add_u32_e32 v132, v1, v54
	ds_write_b32 v132, v100
	v_add_u32_e32 v133, v1, v55
	ds_write_b32 v133, v101
	v_add_u32_e32 v134, v1, v56
	ds_write_b32 v134, v102
	v_add_u32_e32 v135, v1, v57
	ds_write_b32 v135, v103
	v_add_u32_e32 v136, v1, v58
	ds_write_b32 v136, v104
	ds_write_b32 v136, v105 offset:264
	ds_write_b32 v136, v106 offset:528
	ds_write_b32 v136, v107 offset:792
	ds_write_b32 v136, v108 offset:1056
	ds_write_b32 v136, v109 offset:1320
	ds_write_b32 v136, v110 offset:1584
	s_ashr_i32 s21, s20, 31
	v_mov_b32_e32 v137, v111
	v_mov_b32_e32 v10, v136
	v_mov_b32_e32 v17, v137
	s_branch .LBB0_16

.LBB0_383:
	s_add_u32 s16, s40, s28
	s_addc_u32 s17, s41, 0
	s_load_dwordx2 s[30:31], s[16:17], 0x0
	s_load_dwordx2 s[32:33], s[16:17], 0x8
	s_mov_b32 s34, 0
	s_waitcnt lgkmcnt(0)
	s_cmp_gt_i32 s10, 0xffff
	s_cselect_b32 s20, s32, s30
	s_cselect_b32 s21, s33, s31
	s_cselect_b32 s8, 0x10000000, 0
	s_add_u32 s18, s20, s12
	s_addc_u32 s19, s21, s13
	s_sub_u32 s18, s18, s8
	s_subb_u32 s19, s19, 0
	global_load_dwordx4 v[8:11], v1, s[18:19]
	global_load_dwordx4 v[12:15], v1, s[18:19] offset:1024
	global_load_dwordx4 v[16:19], v1, s[18:19] offset:2048
	global_load_dwordx4 v[20:23], v1, s[18:19] offset:3072
	s_mov_b32 s35, s10
	s_add_u32 s10, s10, s0
	s_addc_u32 s11, s11, s1
	s_add_u32 s12, s12, s14
	s_addc_u32 s13, s13, s15
	s_cmp_gt_i32 s10, 0x107ff
	s_cbranch_scc1 .Lxb_lastA
	s_cmp_gt_i32 s10, 0xffff
	s_cselect_b32 s20, s32, s30
	s_cselect_b32 s21, s33, s31
	s_cselect_b32 s8, 0x10000000, 0
	s_add_u32 s18, s20, s12
	s_addc_u32 s19, s21, s13
	s_sub_u32 s18, s18, s8
	s_subb_u32 s19, s19, 0
	global_load_dwordx4 v[50:53], v1, s[18:19]
	global_load_dwordx4 v[54:57], v1, s[18:19] offset:1024
	global_load_dwordx4 v[58:61], v1, s[18:19] offset:2048
	global_load_dwordx4 v[62:65], v1, s[18:19] offset:3072
	s_mov_b32 s36, s10
	s_waitcnt vmcnt(4)
	s_branch .Lxb_procA
.Lxb_lastA:
	s_mov_b32 s34, 1
	s_waitcnt vmcnt(0)
	s_branch .Lxb_procA
.Lxb_topA:
	s_add_u32 s10, s10, s0
	s_addc_u32 s11, s11, s1
	s_add_u32 s12, s12, s14
	s_addc_u32 s13, s13, s15
	s_cmp_gt_i32 s10, 0x107ff
	s_cbranch_scc1 .Lxb_lastA
	s_cmp_gt_i32 s10, 0xffff
	s_cselect_b32 s20, s32, s30
	s_cselect_b32 s21, s33, s31
	s_cselect_b32 s8, 0x10000000, 0
	s_add_u32 s18, s20, s12
	s_addc_u32 s19, s21, s13
	s_sub_u32 s18, s18, s8
	s_subb_u32 s19, s19, 0
	global_load_dwordx4 v[50:53], v1, s[18:19]
	global_load_dwordx4 v[54:57], v1, s[18:19] offset:1024
	global_load_dwordx4 v[58:61], v1, s[18:19] offset:2048
	global_load_dwordx4 v[62:65], v1, s[18:19] offset:3072
	s_mov_b32 s36, s10
	s_waitcnt vmcnt(9)
.Lxb_procA:
	s_mov_b32 s16, s35
	s_mov_b32 s17, 0
	s_lshl_b64 s[18:19], s[16:17], 11
	v_lshl_add_u64 v[24:25], v[6:7], 0, s[18:19]
	v_mul_f32_e32 v5, v9, v9
	v_mul_f32_e32 v26, v11, v11
	v_mul_f32_e32 v27, v13, v13
	v_mul_f32_e32 v28, v15, v15
	v_mul_f32_e32 v29, v17, v17
	v_mul_f32_e32 v30, v19, v19
	v_fmac_f32_e32 v5, v8, v8
	v_fmac_f32_e32 v26, v10, v10
	v_fmac_f32_e32 v27, v12, v12
	v_fmac_f32_e32 v28, v14, v14
	v_mul_f32_e32 v31, v21, v21
	v_mul_f32_e32 v32, v23, v23
	v_fmac_f32_e32 v29, v16, v16
	v_fmac_f32_e32 v30, v18, v18
	v_add_f32_e32 v5, v5, v26
	v_add_f32_e32 v26, v27, v28
	v_fmac_f32_e32 v31, v20, v20
	v_fmac_f32_e32 v32, v22, v22
	v_add_f32_e32 v27, v29, v30
	v_add_f32_e32 v5, v5, v26
	v_add_f32_e32 v28, v31, v32
	v_add_f32_e32 v5, v5, v27
	v_add_f32_e32 v5, v5, v28
	ds_swizzle_b32 v26, v5 offset:swizzle(SWAP,1)
	v_bfe_u32 v33, v8, 16, 1
	v_bfe_u32 v35, v10, 16, 1
	v_bfe_u32 v37, v12, 16, 1
	v_bfe_u32 v41, v16, 16, 1
	s_waitcnt lgkmcnt(0)
	v_add_f32_e32 v5, v5, v26
	ds_swizzle_b32 v26, v5 offset:swizzle(SWAP,2)
	v_bfe_u32 v34, v9, 16, 1
	v_bfe_u32 v36, v11, 16, 1
	v_bfe_u32 v38, v13, 16, 1
	v_bfe_u32 v42, v17, 16, 1
	s_waitcnt lgkmcnt(0)
	v_add_f32_e32 v5, v5, v26
	ds_swizzle_b32 v26, v5 offset:swizzle(SWAP,4)
	v_add3_u32 v8, v8, v33, s25
	v_add3_u32 v10, v10, v35, s25
	v_add3_u32 v12, v12, v37, s25
	v_add3_u32 v16, v16, v41, s25
	s_waitcnt lgkmcnt(0)
	v_add_f32_e32 v5, v5, v26
	ds_swizzle_b32 v26, v5 offset:swizzle(SWAP,8)
	v_add3_u32 v9, v9, v34, s25
	v_add3_u32 v11, v11, v36, s25
	v_add3_u32 v13, v13, v38, s25
	v_add3_u32 v17, v17, v42, s25
	v_lshrrev_b32_e32 v8, 16, v8
	v_lshrrev_b32_e32 v10, 16, v10
	v_lshrrev_b32_e32 v12, 16, v12
	v_lshrrev_b32_e32 v16, 16, v16
	s_waitcnt lgkmcnt(0)
	v_add_f32_e32 v5, v5, v26
	v_and_or_b32 v8, v9, s24, v8
	v_and_or_b32 v9, v11, s24, v10
	v_and_or_b32 v10, v13, s24, v12
	v_and_or_b32 v12, v17, s24, v16
	ds_swizzle_b32 v16, v5 offset:swizzle(SWAP,16)
	v_bfe_u32 v39, v14, 16, 1
	v_bfe_u32 v45, v20, 16, 1
	v_bfe_u32 v47, v22, 16, 1
	v_bfe_u32 v40, v15, 16, 1
	v_bfe_u32 v43, v18, 16, 1
	v_bfe_u32 v46, v21, 16, 1
	v_bfe_u32 v48, v23, 16, 1
	v_add3_u32 v14, v14, v39, s25
	v_add3_u32 v20, v20, v45, s25
	v_add3_u32 v22, v22, v47, s25
	v_bfe_u32 v44, v19, 16, 1
	v_add3_u32 v15, v15, v40, s25
	v_add3_u32 v18, v18, v43, s25
	v_add3_u32 v21, v21, v46, s25
	v_add3_u32 v23, v23, v48, s25
	v_lshrrev_b32_e32 v14, 16, v14
	v_lshrrev_b32_e32 v20, 16, v20
	v_lshrrev_b32_e32 v22, 16, v22
	s_waitcnt lgkmcnt(0)
	v_add_f32_e32 v5, v5, v16
	v_add3_u32 v19, v19, v44, s25
	v_lshrrev_b32_e32 v18, 16, v18
	v_and_or_b32 v11, v15, s24, v14
	v_and_or_b32 v14, v21, s24, v20
	v_and_or_b32 v15, v23, s24, v22
	v_readlane_b32 s8, v5, 0
	v_readlane_b32 s20, v5, 32
	v_and_or_b32 v13, v19, s24, v18
	global_store_dwordx2 v[24:25], v[8:9], off
	global_store_dwordx2 v[24:25], v[10:11], off offset:512
	global_store_dwordx2 v[24:25], v[12:13], off offset:1024
	global_store_dwordx2 v[24:25], v[14:15], off offset:1536
	s_and_saveexec_b64 s[18:19], s[4:5]
	s_lshl_b64 s[16:17], s[16:17], 2
	s_add_u32 s16, s22, s16
	v_mov_b32_e32 v5, s20
	s_addc_u32 s17, s23, s17
	v_add_f32_e32 v5, s8, v5
	global_store_dword v3, v5, s[16:17]
	s_or_b64 exec, exec, s[18:19]
	s_cmp_lg_u32 s34, 0
	s_cbranch_scc1 .LBB0_389
	s_add_u32 s10, s10, s0
	s_addc_u32 s11, s11, s1
	s_add_u32 s12, s12, s14
	s_addc_u32 s13, s13, s15
	s_cmp_gt_i32 s10, 0x107ff
	s_cbranch_scc1 .Lxb_lastB
	s_cmp_gt_i32 s10, 0xffff
	s_cselect_b32 s20, s32, s30
	s_cselect_b32 s21, s33, s31
	s_cselect_b32 s8, 0x10000000, 0
	s_add_u32 s18, s20, s12
	s_addc_u32 s19, s21, s13
	s_sub_u32 s18, s18, s8
	s_subb_u32 s19, s19, 0
	global_load_dwordx4 v[8:11], v1, s[18:19]
	global_load_dwordx4 v[12:15], v1, s[18:19] offset:1024
	global_load_dwordx4 v[16:19], v1, s[18:19] offset:2048
	global_load_dwordx4 v[20:23], v1, s[18:19] offset:3072
	s_mov_b32 s35, s10
	s_waitcnt vmcnt(9)
	s_branch .Lxb_procB
.Lxb_lastB:
	s_mov_b32 s34, 1
	s_waitcnt vmcnt(0)
.Lxb_procB:
	s_mov_b32 s16, s36
	s_mov_b32 s17, 0
	s_lshl_b64 s[18:19], s[16:17], 11
	v_lshl_add_u64 v[24:25], v[6:7], 0, s[18:19]
	v_mul_f32_e32 v5, v51, v51
	v_mul_f32_e32 v26, v53, v53
	v_mul_f32_e32 v27, v55, v55
	v_mul_f32_e32 v28, v57, v57
	v_mul_f32_e32 v29, v59, v59
	v_mul_f32_e32 v30, v61, v61
	v_fmac_f32_e32 v5, v50, v50
	v_fmac_f32_e32 v26, v52, v52
	v_fmac_f32_e32 v27, v54, v54
	v_fmac_f32_e32 v28, v56, v56
	v_mul_f32_e32 v31, v63, v63
	v_mul_f32_e32 v32, v65, v65
	v_fmac_f32_e32 v29, v58, v58
	v_fmac_f32_e32 v30, v60, v60
	v_add_f32_e32 v5, v5, v26
	v_add_f32_e32 v26, v27, v28
	v_fmac_f32_e32 v31, v62, v62
	v_fmac_f32_e32 v32, v64, v64
	v_add_f32_e32 v27, v29, v30
	v_add_f32_e32 v5, v5, v26
	v_add_f32_e32 v28, v31, v32
	v_add_f32_e32 v5, v5, v27
	v_add_f32_e32 v5, v5, v28
	ds_swizzle_b32 v26, v5 offset:swizzle(SWAP,1)
	v_bfe_u32 v33, v50, 16, 1
	v_bfe_u32 v35, v52, 16, 1
	v_bfe_u32 v37, v54, 16, 1
	v_bfe_u32 v41, v58, 16, 1
	s_waitcnt lgkmcnt(0)
	v_add_f32_e32 v5, v5, v26
	ds_swizzle_b32 v26, v5 offset:swizzle(SWAP,2)
	v_bfe_u32 v34, v51, 16, 1
	v_bfe_u32 v36, v53, 16, 1
	v_bfe_u32 v38, v55, 16, 1
	v_bfe_u32 v42, v59, 16, 1
	s_waitcnt lgkmcnt(0)
	v_add_f32_e32 v5, v5, v26
	ds_swizzle_b32 v26, v5 offset:swizzle(SWAP,4)
	v_add3_u32 v50, v50, v33, s25
	v_add3_u32 v52, v52, v35, s25
	v_add3_u32 v54, v54, v37, s25
	v_add3_u32 v58, v58, v41, s25
	s_waitcnt lgkmcnt(0)
	v_add_f32_e32 v5, v5, v26
	ds_swizzle_b32 v26, v5 offset:swizzle(SWAP,8)
	v_add3_u32 v51, v51, v34, s25
	v_add3_u32 v53, v53, v36, s25
	v_add3_u32 v55, v55, v38, s25
	v_add3_u32 v59, v59, v42, s25
	v_lshrrev_b32_e32 v50, 16, v50
	v_lshrrev_b32_e32 v52, 16, v52
	v_lshrrev_b32_e32 v54, 16, v54
	v_lshrrev_b32_e32 v58, 16, v58
	s_waitcnt lgkmcnt(0)
	v_add_f32_e32 v5, v5, v26
	v_and_or_b32 v50, v51, s24, v50
	v_and_or_b32 v51, v53, s24, v52
	v_and_or_b32 v52, v55, s24, v54
	v_and_or_b32 v54, v59, s24, v58
	ds_swizzle_b32 v58, v5 offset:swizzle(SWAP,16)
	v_bfe_u32 v39, v56, 16, 1
	v_bfe_u32 v45, v62, 16, 1
	v_bfe_u32 v47, v64, 16, 1
	v_bfe_u32 v40, v57, 16, 1
	v_bfe_u32 v43, v60, 16, 1
	v_bfe_u32 v46, v63, 16, 1
	v_bfe_u32 v48, v65, 16, 1
	v_add3_u32 v56, v56, v39, s25
	v_add3_u32 v62, v62, v45, s25
	v_add3_u32 v64, v64, v47, s25
	v_bfe_u32 v44, v61, 16, 1
	v_add3_u32 v57, v57, v40, s25
	v_add3_u32 v60, v60, v43, s25
	v_add3_u32 v63, v63, v46, s25
	v_add3_u32 v65, v65, v48, s25
	v_lshrrev_b32_e32 v56, 16, v56
	v_lshrrev_b32_e32 v62, 16, v62
	v_lshrrev_b32_e32 v64, 16, v64
	s_waitcnt lgkmcnt(0)
	v_add_f32_e32 v5, v5, v58
	v_add3_u32 v61, v61, v44, s25
	v_lshrrev_b32_e32 v60, 16, v60
	v_and_or_b32 v53, v57, s24, v56
	v_and_or_b32 v56, v63, s24, v62
	v_and_or_b32 v57, v65, s24, v64
	v_readlane_b32 s8, v5, 0
	v_readlane_b32 s20, v5, 32
	v_and_or_b32 v55, v61, s24, v60
	global_store_dwordx2 v[24:25], v[50:51], off
	global_store_dwordx2 v[24:25], v[52:53], off offset:512
	global_store_dwordx2 v[24:25], v[54:55], off offset:1024
	global_store_dwordx2 v[24:25], v[56:57], off offset:1536
	s_and_saveexec_b64 s[18:19], s[4:5]
	s_lshl_b64 s[16:17], s[16:17], 2
	s_add_u32 s16, s22, s16
	v_mov_b32_e32 v5, s20
	s_addc_u32 s17, s23, s17
	v_add_f32_e32 v5, s8, v5
	global_store_dword v3, v5, s[16:17]
	s_or_b64 exec, exec, s[18:19]
	s_cmp_lg_u32 s34, 0
	s_cbranch_scc0 .Lxb_topA

.LBB0_1671:
	s_cmpk_gt_u32 s29, 0x4ff
	s_cbranch_scc0 .LBB0_1949
	s_cmpk_gt_u32 s29, 0x6ff
	s_cbranch_scc0 .LBB0_1882
	s_cmpk_gt_u32 s29, 0x8ff
	s_cbranch_scc0 .LBB0_1879
	s_cmpk_gt_u32 s29, 0xaff
	s_cbranch_scc0 .LBB0_1812
	s_cmpk_gt_u32 s29, 0xcff
	s_cbranch_scc0 .LBB0_1745
	s_cmpk_gt_u32 s29, 0x14ff
	s_cbranch_scc0 .LBB0_1678
	s_load_dwordx2 s[6:7], s[62:63], 0xc0
	s_lshl_b32 s4, s29, 1
	s_andn2_b32 s4, s4, 63
	s_add_i32 s46, s4, 0xffffd600
	s_lshl_b32 s4, s29, 5
	s_and_b32 s4, s4, 0x3e0
	s_lshl_b32 s5, s4, 2
	s_waitcnt lgkmcnt(0)
	s_add_u32 s6, s6, s5
	s_addc_u32 s7, s7, 0
	v_lshlrev_b32_e32 v2, 2, v4
	v_lshl_add_u64 v[20:21], s[6:7], 0, v[2:3]
	s_mov_b64 s[6:7], 0x1000000
	v_or_b32_e32 v2, s46, v1
	v_lshl_add_u64 v[20:21], v[20:21], 0, s[6:7]
	v_lshlrev_b64 v[22:23], 12, v[2:3]
	v_lshl_add_u64 v[22:23], v[20:21], 0, v[22:23]
	v_or_b32_e32 v2, s46, v25
	global_load_dword v87, v[22:23], off
	v_lshlrev_b64 v[22:23], 12, v[2:3]
	v_lshl_add_u64 v[22:23], v[20:21], 0, v[22:23]
	global_load_dword v88, v[22:23], off
	v_or_b32_e32 v2, s46, v27
	v_lshlrev_b64 v[22:23], 12, v[2:3]
	v_lshl_add_u64 v[22:23], v[20:21], 0, v[22:23]
	v_or_b32_e32 v2, s46, v29
	global_load_dword v89, v[22:23], off
	v_lshlrev_b64 v[22:23], 12, v[2:3]
	v_lshl_add_u64 v[22:23], v[20:21], 0, v[22:23]
	global_load_dword v90, v[22:23], off
	v_or_b32_e32 v2, s46, v31
	v_lshlrev_b64 v[22:23], 12, v[2:3]
	v_lshl_add_u64 v[22:23], v[20:21], 0, v[22:23]
	v_or_b32_e32 v2, s46, v33
	global_load_dword v91, v[22:23], off
	v_lshlrev_b64 v[22:23], 12, v[2:3]
	v_lshl_add_u64 v[22:23], v[20:21], 0, v[22:23]
	global_load_dword v92, v[22:23], off
	v_or_b32_e32 v2, s46, v35
	v_lshlrev_b64 v[22:23], 12, v[2:3]
	v_lshl_add_u64 v[22:23], v[20:21], 0, v[22:23]
	v_or_b32_e32 v2, s46, v37
	global_load_dword v93, v[22:23], off
	v_lshlrev_b64 v[22:23], 12, v[2:3]
	v_lshl_add_u64 v[22:23], v[20:21], 0, v[22:23]
	global_load_dword v94, v[22:23], off
	v_or_b32_e32 v2, s46, v39
	v_lshlrev_b64 v[22:23], 12, v[2:3]
	v_lshl_add_u64 v[22:23], v[20:21], 0, v[22:23]
	v_or_b32_e32 v2, s46, v41
	global_load_dword v95, v[22:23], off
	v_lshlrev_b64 v[22:23], 12, v[2:3]
	v_lshl_add_u64 v[22:23], v[20:21], 0, v[22:23]
	global_load_dword v96, v[22:23], off
	v_or_b32_e32 v2, s46, v43
	v_lshlrev_b64 v[22:23], 12, v[2:3]
	v_lshl_add_u64 v[22:23], v[20:21], 0, v[22:23]
	v_or_b32_e32 v2, s46, v45
	global_load_dword v97, v[22:23], off
	v_lshlrev_b64 v[22:23], 12, v[2:3]
	v_lshl_add_u64 v[22:23], v[20:21], 0, v[22:23]
	global_load_dword v98, v[22:23], off
	v_or_b32_e32 v2, s46, v47
	v_lshlrev_b64 v[22:23], 12, v[2:3]
	v_lshl_add_u64 v[22:23], v[20:21], 0, v[22:23]
	v_or_b32_e32 v2, s46, v49
	global_load_dword v99, v[22:23], off
	v_lshlrev_b64 v[22:23], 12, v[2:3]
	v_lshl_add_u64 v[22:23], v[20:21], 0, v[22:23]
	global_load_dword v100, v[22:23], off
	v_or_b32_e32 v2, s46, v51
	v_lshlrev_b64 v[22:23], 12, v[2:3]
	v_lshl_add_u64 v[22:23], v[20:21], 0, v[22:23]
	v_or_b32_e32 v2, s46, v53
	global_load_dword v101, v[22:23], off
	v_lshlrev_b64 v[22:23], 12, v[2:3]
	v_lshl_add_u64 v[22:23], v[20:21], 0, v[22:23]
	global_load_dword v102, v[22:23], off
	v_or_b32_e32 v2, s46, v55
	v_lshlrev_b64 v[22:23], 12, v[2:3]
	v_lshl_add_u64 v[22:23], v[20:21], 0, v[22:23]
	v_or_b32_e32 v2, s46, v57
	global_load_dword v103, v[22:23], off
	v_lshlrev_b64 v[22:23], 12, v[2:3]
	v_lshl_add_u64 v[22:23], v[20:21], 0, v[22:23]
	global_load_dword v104, v[22:23], off
	v_or_b32_e32 v2, s46, v59
	v_lshlrev_b64 v[22:23], 12, v[2:3]
	v_lshl_add_u64 v[22:23], v[20:21], 0, v[22:23]
	v_or_b32_e32 v2, s46, v61
	global_load_dword v105, v[22:23], off
	v_lshlrev_b64 v[22:23], 12, v[2:3]
	v_lshl_add_u64 v[22:23], v[20:21], 0, v[22:23]
	global_load_dword v148, v[22:23], off
	v_or_b32_e32 v2, s46, v63
	v_lshlrev_b64 v[22:23], 12, v[2:3]
	v_lshl_add_u64 v[22:23], v[20:21], 0, v[22:23]
	v_or_b32_e32 v2, s46, v65
	global_load_dword v149, v[22:23], off
	v_lshlrev_b64 v[22:23], 12, v[2:3]
	v_lshl_add_u64 v[22:23], v[20:21], 0, v[22:23]
	global_load_dword v150, v[22:23], off
	v_or_b32_e32 v2, s46, v67
	v_lshlrev_b64 v[22:23], 12, v[2:3]
	v_lshl_add_u64 v[22:23], v[20:21], 0, v[22:23]
	v_or_b32_e32 v2, s46, v69
	global_load_dword v151, v[22:23], off
	v_lshlrev_b64 v[22:23], 12, v[2:3]
	v_lshl_add_u64 v[22:23], v[20:21], 0, v[22:23]
	global_load_dword v152, v[22:23], off
	v_or_b32_e32 v2, s46, v71
	v_lshlrev_b64 v[22:23], 12, v[2:3]
	v_lshl_add_u64 v[22:23], v[20:21], 0, v[22:23]
	v_or_b32_e32 v2, s46, v73
	global_load_dword v153, v[22:23], off
	v_lshlrev_b64 v[22:23], 12, v[2:3]
	v_lshl_add_u64 v[22:23], v[20:21], 0, v[22:23]
	global_load_dword v154, v[22:23], off
	v_or_b32_e32 v2, s46, v74
	v_lshlrev_b64 v[22:23], 12, v[2:3]
	v_lshl_add_u64 v[22:23], v[20:21], 0, v[22:23]
	v_or_b32_e32 v2, s46, v75
	global_load_dword v155, v[22:23], off
	v_lshlrev_b64 v[22:23], 12, v[2:3]
	v_lshl_add_u64 v[22:23], v[20:21], 0, v[22:23]
	global_load_dword v156, v[22:23], off
	v_or_b32_e32 v2, s46, v76
	v_lshlrev_b64 v[22:23], 12, v[2:3]
	v_lshl_add_u64 v[22:23], v[20:21], 0, v[22:23]
	v_or_b32_e32 v2, s46, v77
	global_load_dword v157, v[22:23], off
	v_lshlrev_b64 v[22:23], 12, v[2:3]
	v_lshl_add_u64 v[22:23], v[20:21], 0, v[22:23]
	global_load_dword v158, v[22:23], off
	v_or_b32_e32 v2, s46, v78
	v_lshlrev_b64 v[22:23], 12, v[2:3]
	v_lshl_add_u64 v[22:23], v[20:21], 0, v[22:23]
	v_or_b32_e32 v2, s46, v79
	global_load_dword v159, v[22:23], off
	v_lshlrev_b64 v[22:23], 12, v[2:3]
	v_lshl_add_u64 v[20:21], v[20:21], 0, v[22:23]
	global_load_dword v160, v[20:21], off
	s_waitcnt vmcnt(0)
	v_add_u32_e32 v161, v5, v24
	ds_write2_b32 v161, v87, v88 offset1:66
	ds_write2_b32 v161, v89, v90 offset0:132 offset1:198
	v_add_u32_e32 v162, 0x400, v161
	v_add_u32_e32 v163, v5, v36
	ds_write2_b32 v162, v91, v92 offset0:8 offset1:74
	ds_write2_b32 v163, v93, v94 offset1:66
	ds_write2_b32 v163, v95, v96 offset0:132 offset1:198
	v_add_u32_e32 v165, 0x400, v163
	v_add_u32_e32 v166, v5, v48
	ds_write2_b32 v165, v97, v98 offset0:8 offset1:74
	ds_write2_b32 v166, v99, v100 offset1:66
	ds_write2_b32 v166, v101, v102 offset0:132 offset1:198
	v_add_u32_e32 v167, 0x400, v166
	v_add_u32_e32 v168, v5, v60
	ds_write2_b32 v167, v103, v104 offset0:8 offset1:74
	ds_write2_b32 v168, v105, v148 offset1:66
	ds_write2_b32 v168, v149, v150 offset0:132 offset1:198
	v_add_u32_e32 v169, 0x400, v168
	v_add_u32_e32 v170, v5, v72
	ds_write2_b32 v169, v151, v152 offset0:8 offset1:74
	ds_write2_b32 v170, v153, v154 offset1:66
	ds_write2_b32 v170, v155, v156 offset0:132 offset1:198
	v_add_u32_e32 v171, 0x400, v170
	ds_write2_b32 v171, v157, v158 offset0:8 offset1:74
	v_lshl_add_u64 v[172:173], s[46:47], 1, v[6:7]
	ds_write2_b32 v171, v159, v160 offset0:140 offset1:206
	v_mov_b32_e32 v20, v172
	v_mov_b32_e32 v21, v173
	s_waitcnt lgkmcnt(0)
	ds_read2_b32 v[22:23], v81 offset0:33 offset1:41
	ds_read2_b32 v[90:91], v81 offset1:8
	ds_read2_b32 v[92:93], v81 offset0:66 offset1:74
	ds_read2_b32 v[94:95], v81 offset0:99 offset1:107
	ds_read2_b32 v[96:97], v81 offset0:132 offset1:140
	ds_read2_b32 v[98:99], v81 offset0:165 offset1:173
	ds_read2_b32 v[100:101], v81 offset0:198 offset1:206
	ds_read2_b32 v[102:103], v81 offset0:231 offset1:239
	s_waitcnt lgkmcnt(7)
	v_bfe_u32 v85, v22, 16, 1
	s_waitcnt lgkmcnt(6)
	v_bfe_u32 v2, v90, 16, 1
	v_add3_u32 v2, v90, v2, s93
	v_lshrrev_b32_e32 v2, 16, v2
	v_add3_u32 v22, v22, v85, s93
	v_and_or_b32 v86, v22, s33, v2
	s_waitcnt lgkmcnt(5)
	v_bfe_u32 v2, v92, 16, 1
	v_add3_u32 v2, v92, v2, s93
	s_waitcnt lgkmcnt(4)
	v_bfe_u32 v22, v94, 16, 1
	v_lshrrev_b32_e32 v2, 16, v2
	v_add3_u32 v22, v94, v22, s93
	v_and_or_b32 v87, v22, s33, v2
	s_waitcnt lgkmcnt(3)
	v_bfe_u32 v2, v96, 16, 1
	v_add3_u32 v2, v96, v2, s93
	s_waitcnt lgkmcnt(2)
	v_bfe_u32 v22, v98, 16, 1
	v_lshrrev_b32_e32 v2, 16, v2
	v_add3_u32 v22, v98, v22, s93
	v_and_or_b32 v88, v22, s33, v2
	s_waitcnt lgkmcnt(1)
	v_bfe_u32 v2, v100, 16, 1
	v_add3_u32 v2, v100, v2, s93
	s_waitcnt lgkmcnt(0)
	v_bfe_u32 v22, v102, 16, 1
	v_lshrrev_b32_e32 v2, 16, v2
	v_add3_u32 v22, v102, v22, s93
	v_and_or_b32 v89, v22, s33, v2
	v_or_b32_e32 v2, s4, v80
	v_lshlrev_b32_e32 v2, 13, v2
	v_lshl_add_u64 v[104:105], v[20:21], 0, v[2:3]
	v_bfe_u32 v2, v91, 16, 1
	v_add3_u32 v2, v91, v2, s93
	v_bfe_u32 v22, v23, 16, 1
	v_lshrrev_b32_e32 v2, 16, v2
	v_add3_u32 v22, v23, v22, s93
	global_store_dwordx4 v[104:105], v[86:89], off
	s_nop 1
	v_and_or_b32 v86, v22, s33, v2
	v_bfe_u32 v2, v93, 16, 1
	v_add3_u32 v2, v93, v2, s93
	v_bfe_u32 v22, v95, 16, 1
	v_lshrrev_b32_e32 v2, 16, v2
	v_add3_u32 v22, v95, v22, s93
	v_and_or_b32 v87, v22, s33, v2
	v_bfe_u32 v2, v97, 16, 1
	v_add3_u32 v2, v97, v2, s93
	v_bfe_u32 v22, v99, 16, 1
	v_lshrrev_b32_e32 v2, 16, v2
	v_add3_u32 v22, v99, v22, s93
	v_and_or_b32 v88, v22, s33, v2
	v_bfe_u32 v2, v101, 16, 1
	v_add3_u32 v2, v101, v2, s93
	v_bfe_u32 v22, v103, 16, 1
	v_lshrrev_b32_e32 v2, 16, v2
	v_add3_u32 v22, v103, v22, s93
	v_and_or_b32 v89, v22, s33, v2
	v_or_b32_e32 v2, s4, v82
	v_lshlrev_b32_e32 v2, 13, v2
	v_lshl_add_u64 v[22:23], v[20:21], 0, v[2:3]
	global_store_dwordx4 v[22:23], v[86:89], off
	ds_read2_b32 v[22:23], v81 offset0:49 offset1:57
	ds_read2_b32 v[90:91], v81 offset0:16 offset1:24
	ds_read2_b32 v[92:93], v81 offset0:82 offset1:90
	ds_read2_b32 v[94:95], v81 offset0:115 offset1:123
	ds_read2_b32 v[96:97], v81 offset0:148 offset1:156
	ds_read2_b32 v[98:99], v81 offset0:181 offset1:189
	ds_read2_b32 v[100:101], v81 offset0:214 offset1:222
	ds_read2_b32 v[102:103], v81 offset0:247 offset1:255
	s_waitcnt lgkmcnt(7)
	v_bfe_u32 v85, v22, 16, 1
	s_waitcnt lgkmcnt(6)
	v_bfe_u32 v2, v90, 16, 1
	v_add3_u32 v2, v90, v2, s93
	v_lshrrev_b32_e32 v2, 16, v2
	v_add3_u32 v22, v22, v85, s93
	v_and_or_b32 v86, v22, s33, v2
	s_waitcnt lgkmcnt(5)
	v_bfe_u32 v2, v92, 16, 1
	v_add3_u32 v2, v92, v2, s93
	s_waitcnt lgkmcnt(4)
	v_bfe_u32 v22, v94, 16, 1
	v_lshrrev_b32_e32 v2, 16, v2
	v_add3_u32 v22, v94, v22, s93
	v_and_or_b32 v87, v22, s33, v2
	s_waitcnt lgkmcnt(3)
	v_bfe_u32 v2, v96, 16, 1
	v_add3_u32 v2, v96, v2, s93
	s_waitcnt lgkmcnt(2)
	v_bfe_u32 v22, v98, 16, 1
	v_lshrrev_b32_e32 v2, 16, v2
	v_add3_u32 v22, v98, v22, s93
	v_and_or_b32 v88, v22, s33, v2
	s_waitcnt lgkmcnt(1)
	v_bfe_u32 v2, v100, 16, 1
	v_add3_u32 v2, v100, v2, s93
	s_waitcnt lgkmcnt(0)
	v_bfe_u32 v22, v102, 16, 1
	v_lshrrev_b32_e32 v2, 16, v2
	v_add3_u32 v22, v102, v22, s93
	v_and_or_b32 v89, v22, s33, v2
	v_or_b32_e32 v2, s4, v83
	v_lshlrev_b32_e32 v2, 13, v2
	v_lshl_add_u64 v[104:105], v[20:21], 0, v[2:3]
	v_bfe_u32 v2, v91, 16, 1
	v_add3_u32 v2, v91, v2, s93
	v_bfe_u32 v22, v23, 16, 1
	v_lshrrev_b32_e32 v2, 16, v2
	v_add3_u32 v22, v23, v22, s93
	global_store_dwordx4 v[104:105], v[86:89], off
	s_nop 1
	v_and_or_b32 v86, v22, s33, v2
	v_bfe_u32 v2, v93, 16, 1
	v_add3_u32 v2, v93, v2, s93
	v_bfe_u32 v22, v95, 16, 1
	v_lshrrev_b32_e32 v2, 16, v2
	v_add3_u32 v22, v95, v22, s93
	v_and_or_b32 v87, v22, s33, v2
	v_bfe_u32 v2, v97, 16, 1
	v_add3_u32 v2, v97, v2, s93
	v_bfe_u32 v22, v99, 16, 1
	v_lshrrev_b32_e32 v2, 16, v2
	v_add3_u32 v22, v99, v22, s93
	v_and_or_b32 v88, v22, s33, v2
	v_bfe_u32 v2, v101, 16, 1
	v_add3_u32 v2, v101, v2, s93
	v_bfe_u32 v22, v103, 16, 1
	v_lshrrev_b32_e32 v2, 16, v2
	v_add3_u32 v22, v103, v22, s93
	v_and_or_b32 v89, v22, s33, v2
	v_or_b32_e32 v2, s4, v84
	v_lshlrev_b32_e32 v2, 13, v2
	v_lshl_add_u64 v[20:21], v[20:21], 0, v[2:3]
	global_store_dwordx4 v[20:21], v[86:89], off
	s_waitcnt lgkmcnt(0)
	s_mov_b64 s[4:5], 0

.LBB0_1879:
	s_andn2_b64 vcc, exec, s[4:5]
	s_cbranch_vccnz .LBB0_1881
	s_load_dwordx2 s[6:7], s[62:63], 0xa8
	s_lshl_b32 s4, s29, 1
	s_add_i32 s4, s4, 0x1f200
	s_and_b32 s5, s4, 0x1ffc0
	s_lshl_b32 s4, s29, 5
	s_and_b32 s4, s4, 0x3e0
	s_lshl_b32 s26, s4, 2
	s_waitcnt lgkmcnt(0)
	s_add_u32 s6, s6, s26
	s_addc_u32 s7, s7, 0
	v_lshlrev_b32_e32 v2, 2, v4
	v_lshl_add_u64 v[20:21], s[6:7], 0, v[2:3]
	v_or_b32_e32 v2, s5, v1
	v_lshl_add_u64 v[20:21], v[20:21], 0, s[96:97]
	v_lshlrev_b32_e32 v2, 12, v2
	v_lshl_add_u64 v[22:23], v[20:21], 0, v[2:3]
	v_or_b32_e32 v2, s5, v25
	v_lshlrev_b32_e32 v2, 12, v2
	global_load_dword v87, v[22:23], off
	v_lshl_add_u64 v[22:23], v[20:21], 0, v[2:3]
	global_load_dword v88, v[22:23], off
	v_or_b32_e32 v2, s5, v27
	v_lshlrev_b32_e32 v2, 12, v2
	v_lshl_add_u64 v[22:23], v[20:21], 0, v[2:3]
	v_or_b32_e32 v2, s5, v29
	v_lshlrev_b32_e32 v2, 12, v2
	global_load_dword v89, v[22:23], off
	v_lshl_add_u64 v[22:23], v[20:21], 0, v[2:3]
	global_load_dword v90, v[22:23], off
	v_or_b32_e32 v2, s5, v31
	v_lshlrev_b32_e32 v2, 12, v2
	v_lshl_add_u64 v[22:23], v[20:21], 0, v[2:3]
	v_or_b32_e32 v2, s5, v33
	v_lshlrev_b32_e32 v2, 12, v2
	global_load_dword v91, v[22:23], off
	v_lshl_add_u64 v[22:23], v[20:21], 0, v[2:3]
	global_load_dword v92, v[22:23], off
	v_or_b32_e32 v2, s5, v35
	v_lshlrev_b32_e32 v2, 12, v2
	v_lshl_add_u64 v[22:23], v[20:21], 0, v[2:3]
	v_or_b32_e32 v2, s5, v37
	v_lshlrev_b32_e32 v2, 12, v2
	global_load_dword v93, v[22:23], off
	v_lshl_add_u64 v[22:23], v[20:21], 0, v[2:3]
	global_load_dword v94, v[22:23], off
	v_or_b32_e32 v2, s5, v39
	v_lshlrev_b32_e32 v2, 12, v2
	v_lshl_add_u64 v[22:23], v[20:21], 0, v[2:3]
	v_or_b32_e32 v2, s5, v41
	v_lshlrev_b32_e32 v2, 12, v2
	global_load_dword v95, v[22:23], off
	v_lshl_add_u64 v[22:23], v[20:21], 0, v[2:3]
	global_load_dword v96, v[22:23], off
	v_or_b32_e32 v2, s5, v43
	v_lshlrev_b32_e32 v2, 12, v2
	v_lshl_add_u64 v[22:23], v[20:21], 0, v[2:3]
	v_or_b32_e32 v2, s5, v45
	v_lshlrev_b32_e32 v2, 12, v2
	global_load_dword v97, v[22:23], off
	v_lshl_add_u64 v[22:23], v[20:21], 0, v[2:3]
	global_load_dword v98, v[22:23], off
	v_or_b32_e32 v2, s5, v47
	v_lshlrev_b32_e32 v2, 12, v2
	v_lshl_add_u64 v[22:23], v[20:21], 0, v[2:3]
	v_or_b32_e32 v2, s5, v49
	v_lshlrev_b32_e32 v2, 12, v2
	global_load_dword v99, v[22:23], off
	v_lshl_add_u64 v[22:23], v[20:21], 0, v[2:3]
	global_load_dword v100, v[22:23], off
	v_or_b32_e32 v2, s5, v51
	v_lshlrev_b32_e32 v2, 12, v2
	v_lshl_add_u64 v[22:23], v[20:21], 0, v[2:3]
	v_or_b32_e32 v2, s5, v53
	v_lshlrev_b32_e32 v2, 12, v2
	global_load_dword v101, v[22:23], off
	v_lshl_add_u64 v[22:23], v[20:21], 0, v[2:3]
	global_load_dword v102, v[22:23], off
	v_or_b32_e32 v2, s5, v55
	v_lshlrev_b32_e32 v2, 12, v2
	v_lshl_add_u64 v[22:23], v[20:21], 0, v[2:3]
	v_or_b32_e32 v2, s5, v57
	v_lshlrev_b32_e32 v2, 12, v2
	global_load_dword v103, v[22:23], off
	v_lshl_add_u64 v[22:23], v[20:21], 0, v[2:3]
	global_load_dword v104, v[22:23], off
	v_or_b32_e32 v2, s5, v59
	v_lshlrev_b32_e32 v2, 12, v2
	v_lshl_add_u64 v[22:23], v[20:21], 0, v[2:3]
	v_or_b32_e32 v2, s5, v61
	v_lshlrev_b32_e32 v2, 12, v2
	global_load_dword v105, v[22:23], off
	v_lshl_add_u64 v[22:23], v[20:21], 0, v[2:3]
	global_load_dword v148, v[22:23], off
	v_or_b32_e32 v2, s5, v63
	v_lshlrev_b32_e32 v2, 12, v2
	v_lshl_add_u64 v[22:23], v[20:21], 0, v[2:3]
	v_or_b32_e32 v2, s5, v65
	v_lshlrev_b32_e32 v2, 12, v2
	global_load_dword v149, v[22:23], off
	v_lshl_add_u64 v[22:23], v[20:21], 0, v[2:3]
	global_load_dword v150, v[22:23], off
	v_or_b32_e32 v2, s5, v67
	v_lshlrev_b32_e32 v2, 12, v2
	v_lshl_add_u64 v[22:23], v[20:21], 0, v[2:3]
	v_or_b32_e32 v2, s5, v69
	v_lshlrev_b32_e32 v2, 12, v2
	global_load_dword v151, v[22:23], off
	v_lshl_add_u64 v[22:23], v[20:21], 0, v[2:3]
	global_load_dword v152, v[22:23], off
	v_or_b32_e32 v2, s5, v71
	v_lshlrev_b32_e32 v2, 12, v2
	v_lshl_add_u64 v[22:23], v[20:21], 0, v[2:3]
	v_or_b32_e32 v2, s5, v73
	v_lshlrev_b32_e32 v2, 12, v2
	global_load_dword v153, v[22:23], off
	v_lshl_add_u64 v[22:23], v[20:21], 0, v[2:3]
	global_load_dword v154, v[22:23], off
	v_or_b32_e32 v2, s5, v74
	v_lshlrev_b32_e32 v2, 12, v2
	v_lshl_add_u64 v[22:23], v[20:21], 0, v[2:3]
	v_or_b32_e32 v2, s5, v75
	v_lshlrev_b32_e32 v2, 12, v2
	global_load_dword v155, v[22:23], off
	v_lshl_add_u64 v[22:23], v[20:21], 0, v[2:3]
	global_load_dword v156, v[22:23], off
	v_or_b32_e32 v2, s5, v76
	v_lshlrev_b32_e32 v2, 12, v2
	v_lshl_add_u64 v[22:23], v[20:21], 0, v[2:3]
	v_or_b32_e32 v2, s5, v77
	v_lshlrev_b32_e32 v2, 12, v2
	global_load_dword v157, v[22:23], off
	v_lshl_add_u64 v[22:23], v[20:21], 0, v[2:3]
	global_load_dword v158, v[22:23], off
	v_or_b32_e32 v2, s5, v78
	v_lshlrev_b32_e32 v2, 12, v2
	v_lshl_add_u64 v[22:23], v[20:21], 0, v[2:3]
	v_or_b32_e32 v2, s5, v79
	v_lshlrev_b32_e32 v2, 12, v2
	v_lshl_add_u64 v[20:21], v[20:21], 0, v[2:3]
	global_load_dword v159, v[22:23], off
	global_load_dword v160, v[20:21], off
	s_waitcnt vmcnt(0)
	v_add_u32_e32 v161, v5, v24
	s_lshl_b32 s46, s5, 1
	ds_write2_b32 v161, v87, v88 offset1:66
	ds_write2_b32 v161, v89, v90 offset0:132 offset1:198
	v_add_u32_e32 v162, 0x400, v161
	v_add_u32_e32 v163, v5, v36
	ds_write2_b32 v162, v91, v92 offset0:8 offset1:74
	ds_write2_b32 v163, v93, v94 offset1:66
	ds_write2_b32 v163, v95, v96 offset0:132 offset1:198
	v_add_u32_e32 v165, 0x400, v163
	v_add_u32_e32 v166, v5, v48
	ds_write2_b32 v165, v97, v98 offset0:8 offset1:74
	ds_write2_b32 v166, v99, v100 offset1:66
	ds_write2_b32 v166, v101, v102 offset0:132 offset1:198
	v_add_u32_e32 v167, 0x400, v166
	v_add_u32_e32 v168, v5, v60
	ds_write2_b32 v167, v103, v104 offset0:8 offset1:74
	ds_write2_b32 v168, v105, v148 offset1:66
	ds_write2_b32 v168, v149, v150 offset0:132 offset1:198
	v_add_u32_e32 v169, 0x400, v168
	v_add_u32_e32 v170, v5, v72
	ds_write2_b32 v169, v151, v152 offset0:8 offset1:74
	ds_write2_b32 v170, v153, v154 offset1:66
	ds_write2_b32 v170, v155, v156 offset0:132 offset1:198
	v_add_u32_e32 v171, 0x400, v170
	ds_write2_b32 v171, v157, v158 offset0:8 offset1:74
	s_nop 0
	v_lshl_add_u64 v[172:173], v[12:13], 0, s[46:47]
	ds_write2_b32 v171, v159, v160 offset0:140 offset1:206
	v_mov_b32_e32 v20, v172
	v_mov_b32_e32 v21, v173
	s_waitcnt lgkmcnt(0)
	ds_read2_b32 v[22:23], v81 offset0:33 offset1:41
	ds_read2_b32 v[90:91], v81 offset1:8
	ds_read2_b32 v[92:93], v81 offset0:66 offset1:74
	ds_read2_b32 v[94:95], v81 offset0:99 offset1:107
	ds_read2_b32 v[96:97], v81 offset0:132 offset1:140
	ds_read2_b32 v[98:99], v81 offset0:165 offset1:173
	ds_read2_b32 v[100:101], v81 offset0:198 offset1:206
	ds_read2_b32 v[102:103], v81 offset0:231 offset1:239
	s_waitcnt lgkmcnt(7)
	v_bfe_u32 v85, v22, 16, 1
	s_waitcnt lgkmcnt(6)
	v_bfe_u32 v2, v90, 16, 1
	v_add3_u32 v2, v90, v2, s93
	v_lshrrev_b32_e32 v2, 16, v2
	v_add3_u32 v22, v22, v85, s93
	v_and_or_b32 v86, v22, s33, v2
	s_waitcnt lgkmcnt(5)
	v_bfe_u32 v2, v92, 16, 1
	v_add3_u32 v2, v92, v2, s93
	s_waitcnt lgkmcnt(4)
	v_bfe_u32 v22, v94, 16, 1
	v_lshrrev_b32_e32 v2, 16, v2
	v_add3_u32 v22, v94, v22, s93
	v_and_or_b32 v87, v22, s33, v2
	s_waitcnt lgkmcnt(3)
	v_bfe_u32 v2, v96, 16, 1
	v_add3_u32 v2, v96, v2, s93
	s_waitcnt lgkmcnt(2)
	v_bfe_u32 v22, v98, 16, 1
	v_lshrrev_b32_e32 v2, 16, v2
	v_add3_u32 v22, v98, v22, s93
	v_and_or_b32 v88, v22, s33, v2
	s_waitcnt lgkmcnt(1)
	v_bfe_u32 v2, v100, 16, 1
	v_add3_u32 v2, v100, v2, s93
	s_waitcnt lgkmcnt(0)
	v_bfe_u32 v22, v102, 16, 1
	v_lshrrev_b32_e32 v2, 16, v2
	v_add3_u32 v22, v102, v22, s93
	v_and_or_b32 v89, v22, s33, v2
	v_or_b32_e32 v2, s4, v80
	v_lshlrev_b32_e32 v2, 11, v2
	v_lshl_add_u64 v[104:105], v[20:21], 0, v[2:3]
	v_bfe_u32 v2, v91, 16, 1
	v_add3_u32 v2, v91, v2, s93
	v_bfe_u32 v22, v23, 16, 1
	v_lshrrev_b32_e32 v2, 16, v2
	v_add3_u32 v22, v23, v22, s93
	global_store_dwordx4 v[104:105], v[86:89], off
	s_nop 1
	v_and_or_b32 v86, v22, s33, v2
	v_bfe_u32 v2, v93, 16, 1
	v_add3_u32 v2, v93, v2, s93
	v_bfe_u32 v22, v95, 16, 1
	v_lshrrev_b32_e32 v2, 16, v2
	v_add3_u32 v22, v95, v22, s93
	v_and_or_b32 v87, v22, s33, v2
	v_bfe_u32 v2, v97, 16, 1
	v_add3_u32 v2, v97, v2, s93
	v_bfe_u32 v22, v99, 16, 1
	v_lshrrev_b32_e32 v2, 16, v2
	v_add3_u32 v22, v99, v22, s93
	v_and_or_b32 v88, v22, s33, v2
	v_bfe_u32 v2, v101, 16, 1
	v_add3_u32 v2, v101, v2, s93
	v_bfe_u32 v22, v103, 16, 1
	v_lshrrev_b32_e32 v2, 16, v2
	v_add3_u32 v22, v103, v22, s93
	v_and_or_b32 v89, v22, s33, v2
	v_or_b32_e32 v2, s4, v82
	v_lshlrev_b32_e32 v2, 11, v2
	v_lshl_add_u64 v[22:23], v[20:21], 0, v[2:3]
	global_store_dwordx4 v[22:23], v[86:89], off
	ds_read2_b32 v[22:23], v81 offset0:49 offset1:57
	ds_read2_b32 v[90:91], v81 offset0:16 offset1:24
	ds_read2_b32 v[92:93], v81 offset0:82 offset1:90
	ds_read2_b32 v[94:95], v81 offset0:115 offset1:123
	ds_read2_b32 v[96:97], v81 offset0:148 offset1:156
	ds_read2_b32 v[98:99], v81 offset0:181 offset1:189
	ds_read2_b32 v[100:101], v81 offset0:214 offset1:222
	ds_read2_b32 v[102:103], v81 offset0:247 offset1:255
	s_waitcnt lgkmcnt(7)
	v_bfe_u32 v85, v22, 16, 1
	s_waitcnt lgkmcnt(6)
	v_bfe_u32 v2, v90, 16, 1
	v_add3_u32 v2, v90, v2, s93
	v_lshrrev_b32_e32 v2, 16, v2
	v_add3_u32 v22, v22, v85, s93
	v_and_or_b32 v86, v22, s33, v2
	s_waitcnt lgkmcnt(5)
	v_bfe_u32 v2, v92, 16, 1
	v_add3_u32 v2, v92, v2, s93
	s_waitcnt lgkmcnt(4)
	v_bfe_u32 v22, v94, 16, 1
	v_lshrrev_b32_e32 v2, 16, v2
	v_add3_u32 v22, v94, v22, s93
	v_and_or_b32 v87, v22, s33, v2
	s_waitcnt lgkmcnt(3)
	v_bfe_u32 v2, v96, 16, 1
	v_add3_u32 v2, v96, v2, s93
	s_waitcnt lgkmcnt(2)
	v_bfe_u32 v22, v98, 16, 1
	v_lshrrev_b32_e32 v2, 16, v2
	v_add3_u32 v22, v98, v22, s93
	v_and_or_b32 v88, v22, s33, v2
	s_waitcnt lgkmcnt(1)
	v_bfe_u32 v2, v100, 16, 1
	v_add3_u32 v2, v100, v2, s93
	s_waitcnt lgkmcnt(0)
	v_bfe_u32 v22, v102, 16, 1
	v_lshrrev_b32_e32 v2, 16, v2
	v_add3_u32 v22, v102, v22, s93
	v_and_or_b32 v89, v22, s33, v2
	v_or_b32_e32 v2, s4, v83
	v_lshlrev_b32_e32 v2, 11, v2
	v_lshl_add_u64 v[104:105], v[20:21], 0, v[2:3]
	v_bfe_u32 v2, v91, 16, 1
	v_add3_u32 v2, v91, v2, s93
	v_bfe_u32 v22, v23, 16, 1
	v_lshrrev_b32_e32 v2, 16, v2
	v_add3_u32 v22, v23, v22, s93
	global_store_dwordx4 v[104:105], v[86:89], off
	s_nop 1
	v_and_or_b32 v86, v22, s33, v2
	v_bfe_u32 v2, v93, 16, 1
	v_add3_u32 v2, v93, v2, s93
	v_bfe_u32 v22, v95, 16, 1
	v_lshrrev_b32_e32 v2, 16, v2
	v_add3_u32 v22, v95, v22, s93
	v_and_or_b32 v87, v22, s33, v2
	v_bfe_u32 v2, v97, 16, 1
	v_add3_u32 v2, v97, v2, s93
	v_bfe_u32 v22, v99, 16, 1
	v_lshrrev_b32_e32 v2, 16, v2
	v_add3_u32 v22, v99, v22, s93
	v_and_or_b32 v88, v22, s33, v2
	v_bfe_u32 v2, v101, 16, 1
	v_add3_u32 v2, v101, v2, s93
	v_bfe_u32 v22, v103, 16, 1
	v_lshrrev_b32_e32 v2, 16, v2
	v_add3_u32 v22, v103, v22, s93
	v_and_or_b32 v89, v22, s33, v2
	v_or_b32_e32 v2, s4, v84
	v_lshlrev_b32_e32 v2, 11, v2
	v_lshl_add_u64 v[20:21], v[20:21], 0, v[2:3]
	global_store_dwordx4 v[20:21], v[86:89], off
	s_waitcnt lgkmcnt(0)

.LBB0_1949:
	s_andn2_b64 vcc, exec, s[4:5]
	s_cbranch_vccnz .LBB0_1951
	s_load_dwordx2 s[6:7], s[62:63], 0x78
	s_lshl_b32 s4, s29, 1
	s_and_b32 s5, s4, 0x1c0
	s_lshl_b32 s4, s29, 5
	s_and_b32 s4, s4, 0x3e0
	s_lshl_b32 s26, s4, 2
	s_waitcnt lgkmcnt(0)
	s_add_u32 s6, s6, s26
	s_addc_u32 s7, s7, 0
	v_lshlrev_b32_e32 v2, 2, v4
	v_lshl_add_u64 v[20:21], s[6:7], 0, v[2:3]
	v_or_b32_e32 v2, s5, v1
	v_lshl_add_u64 v[20:21], v[20:21], 0, s[96:97]
	v_lshlrev_b32_e32 v2, 12, v2
	v_lshl_add_u64 v[22:23], v[20:21], 0, v[2:3]
	v_or_b32_e32 v2, s5, v25
	v_lshlrev_b32_e32 v2, 12, v2
	global_load_dword v87, v[22:23], off
	v_lshl_add_u64 v[22:23], v[20:21], 0, v[2:3]
	global_load_dword v88, v[22:23], off
	v_or_b32_e32 v2, s5, v27
	v_lshlrev_b32_e32 v2, 12, v2
	v_lshl_add_u64 v[22:23], v[20:21], 0, v[2:3]
	v_or_b32_e32 v2, s5, v29
	v_lshlrev_b32_e32 v2, 12, v2
	global_load_dword v89, v[22:23], off
	v_lshl_add_u64 v[22:23], v[20:21], 0, v[2:3]
	global_load_dword v90, v[22:23], off
	v_or_b32_e32 v2, s5, v31
	v_lshlrev_b32_e32 v2, 12, v2
	v_lshl_add_u64 v[22:23], v[20:21], 0, v[2:3]
	v_or_b32_e32 v2, s5, v33
	v_lshlrev_b32_e32 v2, 12, v2
	global_load_dword v91, v[22:23], off
	v_lshl_add_u64 v[22:23], v[20:21], 0, v[2:3]
	global_load_dword v92, v[22:23], off
	v_or_b32_e32 v2, s5, v35
	v_lshlrev_b32_e32 v2, 12, v2
	v_lshl_add_u64 v[22:23], v[20:21], 0, v[2:3]
	v_or_b32_e32 v2, s5, v37
	v_lshlrev_b32_e32 v2, 12, v2
	global_load_dword v93, v[22:23], off
	v_lshl_add_u64 v[22:23], v[20:21], 0, v[2:3]
	global_load_dword v94, v[22:23], off
	v_or_b32_e32 v2, s5, v39
	v_lshlrev_b32_e32 v2, 12, v2
	v_lshl_add_u64 v[22:23], v[20:21], 0, v[2:3]
	v_or_b32_e32 v2, s5, v41
	v_lshlrev_b32_e32 v2, 12, v2
	global_load_dword v95, v[22:23], off
	v_lshl_add_u64 v[22:23], v[20:21], 0, v[2:3]
	global_load_dword v96, v[22:23], off
	v_or_b32_e32 v2, s5, v43
	v_lshlrev_b32_e32 v2, 12, v2
	v_lshl_add_u64 v[22:23], v[20:21], 0, v[2:3]
	v_or_b32_e32 v2, s5, v45
	v_lshlrev_b32_e32 v2, 12, v2
	global_load_dword v97, v[22:23], off
	v_lshl_add_u64 v[22:23], v[20:21], 0, v[2:3]
	global_load_dword v98, v[22:23], off
	v_or_b32_e32 v2, s5, v47
	v_lshlrev_b32_e32 v2, 12, v2
	v_lshl_add_u64 v[22:23], v[20:21], 0, v[2:3]
	v_or_b32_e32 v2, s5, v49
	v_lshlrev_b32_e32 v2, 12, v2
	global_load_dword v99, v[22:23], off
	v_lshl_add_u64 v[22:23], v[20:21], 0, v[2:3]
	global_load_dword v100, v[22:23], off
	v_or_b32_e32 v2, s5, v51
	v_lshlrev_b32_e32 v2, 12, v2
	v_lshl_add_u64 v[22:23], v[20:21], 0, v[2:3]
	v_or_b32_e32 v2, s5, v53
	v_lshlrev_b32_e32 v2, 12, v2
	global_load_dword v101, v[22:23], off
	v_lshl_add_u64 v[22:23], v[20:21], 0, v[2:3]
	global_load_dword v102, v[22:23], off
	v_or_b32_e32 v2, s5, v55
	v_lshlrev_b32_e32 v2, 12, v2
	v_lshl_add_u64 v[22:23], v[20:21], 0, v[2:3]
	v_or_b32_e32 v2, s5, v57
	v_lshlrev_b32_e32 v2, 12, v2
	global_load_dword v103, v[22:23], off
	v_lshl_add_u64 v[22:23], v[20:21], 0, v[2:3]
	global_load_dword v104, v[22:23], off
	v_or_b32_e32 v2, s5, v59
	v_lshlrev_b32_e32 v2, 12, v2
	v_lshl_add_u64 v[22:23], v[20:21], 0, v[2:3]
	v_or_b32_e32 v2, s5, v61
	v_lshlrev_b32_e32 v2, 12, v2
	global_load_dword v105, v[22:23], off
	v_lshl_add_u64 v[22:23], v[20:21], 0, v[2:3]
	global_load_dword v148, v[22:23], off
	v_or_b32_e32 v2, s5, v63
	v_lshlrev_b32_e32 v2, 12, v2
	v_lshl_add_u64 v[22:23], v[20:21], 0, v[2:3]
	v_or_b32_e32 v2, s5, v65
	v_lshlrev_b32_e32 v2, 12, v2
	global_load_dword v149, v[22:23], off
	v_lshl_add_u64 v[22:23], v[20:21], 0, v[2:3]
	global_load_dword v150, v[22:23], off
	v_or_b32_e32 v2, s5, v67
	v_lshlrev_b32_e32 v2, 12, v2
	v_lshl_add_u64 v[22:23], v[20:21], 0, v[2:3]
	v_or_b32_e32 v2, s5, v69
	v_lshlrev_b32_e32 v2, 12, v2
	global_load_dword v151, v[22:23], off
	v_lshl_add_u64 v[22:23], v[20:21], 0, v[2:3]
	global_load_dword v152, v[22:23], off
	v_or_b32_e32 v2, s5, v71
	v_lshlrev_b32_e32 v2, 12, v2
	v_lshl_add_u64 v[22:23], v[20:21], 0, v[2:3]
	v_or_b32_e32 v2, s5, v73
	v_lshlrev_b32_e32 v2, 12, v2
	global_load_dword v153, v[22:23], off
	v_lshl_add_u64 v[22:23], v[20:21], 0, v[2:3]
	global_load_dword v154, v[22:23], off
	v_or_b32_e32 v2, s5, v74
	v_lshlrev_b32_e32 v2, 12, v2
	v_lshl_add_u64 v[22:23], v[20:21], 0, v[2:3]
	v_or_b32_e32 v2, s5, v75
	v_lshlrev_b32_e32 v2, 12, v2
	global_load_dword v155, v[22:23], off
	v_lshl_add_u64 v[22:23], v[20:21], 0, v[2:3]
	global_load_dword v156, v[22:23], off
	v_or_b32_e32 v2, s5, v76
	v_lshlrev_b32_e32 v2, 12, v2
	v_lshl_add_u64 v[22:23], v[20:21], 0, v[2:3]
	v_or_b32_e32 v2, s5, v77
	v_lshlrev_b32_e32 v2, 12, v2
	global_load_dword v157, v[22:23], off
	v_lshl_add_u64 v[22:23], v[20:21], 0, v[2:3]
	global_load_dword v158, v[22:23], off
	v_or_b32_e32 v2, s5, v78
	v_lshlrev_b32_e32 v2, 12, v2
	v_lshl_add_u64 v[22:23], v[20:21], 0, v[2:3]
	v_or_b32_e32 v2, s5, v79
	v_lshlrev_b32_e32 v2, 12, v2
	v_lshl_add_u64 v[20:21], v[20:21], 0, v[2:3]
	global_load_dword v159, v[22:23], off
	global_load_dword v160, v[20:21], off
	s_waitcnt vmcnt(0)
	v_add_u32_e32 v161, v5, v24
	s_lshl_b32 s46, s5, 1
	ds_write2_b32 v161, v87, v88 offset1:66
	ds_write2_b32 v161, v89, v90 offset0:132 offset1:198
	v_add_u32_e32 v162, 0x400, v161
	v_add_u32_e32 v163, v5, v36
	ds_write2_b32 v162, v91, v92 offset0:8 offset1:74
	ds_write2_b32 v163, v93, v94 offset1:66
	ds_write2_b32 v163, v95, v96 offset0:132 offset1:198
	v_add_u32_e32 v165, 0x400, v163
	v_add_u32_e32 v166, v5, v48
	ds_write2_b32 v165, v97, v98 offset0:8 offset1:74
	ds_write2_b32 v166, v99, v100 offset1:66
	ds_write2_b32 v166, v101, v102 offset0:132 offset1:198
	v_add_u32_e32 v167, 0x400, v166
	v_add_u32_e32 v168, v5, v60
	ds_write2_b32 v167, v103, v104 offset0:8 offset1:74
	ds_write2_b32 v168, v105, v148 offset1:66
	ds_write2_b32 v168, v149, v150 offset0:132 offset1:198
	v_add_u32_e32 v169, 0x400, v168
	v_add_u32_e32 v170, v5, v72
	ds_write2_b32 v169, v151, v152 offset0:8 offset1:74
	ds_write2_b32 v170, v153, v154 offset1:66
	ds_write2_b32 v170, v155, v156 offset0:132 offset1:198
	v_add_u32_e32 v171, 0x400, v170
	ds_write2_b32 v171, v157, v158 offset0:8 offset1:74
	s_nop 0
	v_lshl_add_u64 v[172:173], v[16:17], 0, s[46:47]
	ds_write2_b32 v171, v159, v160 offset0:140 offset1:206
	v_mov_b32_e32 v20, v172
	v_mov_b32_e32 v21, v173
	s_waitcnt lgkmcnt(0)
	ds_read2_b32 v[22:23], v81 offset0:33 offset1:41
	ds_read2_b32 v[90:91], v81 offset1:8
	ds_read2_b32 v[92:93], v81 offset0:66 offset1:74
	ds_read2_b32 v[94:95], v81 offset0:99 offset1:107
	ds_read2_b32 v[96:97], v81 offset0:132 offset1:140
	ds_read2_b32 v[98:99], v81 offset0:165 offset1:173
	ds_read2_b32 v[100:101], v81 offset0:198 offset1:206
	ds_read2_b32 v[102:103], v81 offset0:231 offset1:239
	s_waitcnt lgkmcnt(7)
	v_bfe_u32 v85, v22, 16, 1
	s_waitcnt lgkmcnt(6)
	v_bfe_u32 v2, v90, 16, 1
	v_add3_u32 v2, v90, v2, s93
	v_lshrrev_b32_e32 v2, 16, v2
	v_add3_u32 v22, v22, v85, s93
	v_and_or_b32 v86, v22, s33, v2
	s_waitcnt lgkmcnt(5)
	v_bfe_u32 v2, v92, 16, 1
	v_add3_u32 v2, v92, v2, s93
	s_waitcnt lgkmcnt(4)
	v_bfe_u32 v22, v94, 16, 1
	v_lshrrev_b32_e32 v2, 16, v2
	v_add3_u32 v22, v94, v22, s93
	v_and_or_b32 v87, v22, s33, v2
	s_waitcnt lgkmcnt(3)
	v_bfe_u32 v2, v96, 16, 1
	v_add3_u32 v2, v96, v2, s93
	s_waitcnt lgkmcnt(2)
	v_bfe_u32 v22, v98, 16, 1
	v_lshrrev_b32_e32 v2, 16, v2
	v_add3_u32 v22, v98, v22, s93
	v_and_or_b32 v88, v22, s33, v2
	s_waitcnt lgkmcnt(1)
	v_bfe_u32 v2, v100, 16, 1
	v_add3_u32 v2, v100, v2, s93
	s_waitcnt lgkmcnt(0)
	v_bfe_u32 v22, v102, 16, 1
	v_lshrrev_b32_e32 v2, 16, v2
	v_add3_u32 v22, v102, v22, s93
	v_and_or_b32 v89, v22, s33, v2
	v_or_b32_e32 v2, s4, v80
	v_lshlrev_b32_e32 v2, 11, v2
	v_lshl_add_u64 v[104:105], v[20:21], 0, v[2:3]
	v_bfe_u32 v2, v91, 16, 1
	v_add3_u32 v2, v91, v2, s93
	v_bfe_u32 v22, v23, 16, 1
	v_lshrrev_b32_e32 v2, 16, v2
	v_add3_u32 v22, v23, v22, s93
	global_store_dwordx4 v[104:105], v[86:89], off
	s_nop 1
	v_and_or_b32 v86, v22, s33, v2
	v_bfe_u32 v2, v93, 16, 1
	v_add3_u32 v2, v93, v2, s93
	v_bfe_u32 v22, v95, 16, 1
	v_lshrrev_b32_e32 v2, 16, v2
	v_add3_u32 v22, v95, v22, s93
	v_and_or_b32 v87, v22, s33, v2
	v_bfe_u32 v2, v97, 16, 1
	v_add3_u32 v2, v97, v2, s93
	v_bfe_u32 v22, v99, 16, 1
	v_lshrrev_b32_e32 v2, 16, v2
	v_add3_u32 v22, v99, v22, s93
	v_and_or_b32 v88, v22, s33, v2
	v_bfe_u32 v2, v101, 16, 1
	v_add3_u32 v2, v101, v2, s93
	v_bfe_u32 v22, v103, 16, 1
	v_lshrrev_b32_e32 v2, 16, v2
	v_add3_u32 v22, v103, v22, s93
	v_and_or_b32 v89, v22, s33, v2
	v_or_b32_e32 v2, s4, v82
	v_lshlrev_b32_e32 v2, 11, v2
	v_lshl_add_u64 v[22:23], v[20:21], 0, v[2:3]
	global_store_dwordx4 v[22:23], v[86:89], off
	ds_read2_b32 v[22:23], v81 offset0:49 offset1:57
	ds_read2_b32 v[90:91], v81 offset0:16 offset1:24
	ds_read2_b32 v[92:93], v81 offset0:82 offset1:90
	ds_read2_b32 v[94:95], v81 offset0:115 offset1:123
	ds_read2_b32 v[96:97], v81 offset0:148 offset1:156
	ds_read2_b32 v[98:99], v81 offset0:181 offset1:189
	ds_read2_b32 v[100:101], v81 offset0:214 offset1:222
	ds_read2_b32 v[102:103], v81 offset0:247 offset1:255
	s_waitcnt lgkmcnt(7)
	v_bfe_u32 v85, v22, 16, 1
	s_waitcnt lgkmcnt(6)
	v_bfe_u32 v2, v90, 16, 1
	v_add3_u32 v2, v90, v2, s93
	v_lshrrev_b32_e32 v2, 16, v2
	v_add3_u32 v22, v22, v85, s93
	v_and_or_b32 v86, v22, s33, v2
	s_waitcnt lgkmcnt(5)
	v_bfe_u32 v2, v92, 16, 1
	v_add3_u32 v2, v92, v2, s93
	s_waitcnt lgkmcnt(4)
	v_bfe_u32 v22, v94, 16, 1
	v_lshrrev_b32_e32 v2, 16, v2
	v_add3_u32 v22, v94, v22, s93
	v_and_or_b32 v87, v22, s33, v2
	s_waitcnt lgkmcnt(3)
	v_bfe_u32 v2, v96, 16, 1
	v_add3_u32 v2, v96, v2, s93
	s_waitcnt lgkmcnt(2)
	v_bfe_u32 v22, v98, 16, 1
	v_lshrrev_b32_e32 v2, 16, v2
	v_add3_u32 v22, v98, v22, s93
	v_and_or_b32 v88, v22, s33, v2
	s_waitcnt lgkmcnt(1)
	v_bfe_u32 v2, v100, 16, 1
	v_add3_u32 v2, v100, v2, s93
	s_waitcnt lgkmcnt(0)
	v_bfe_u32 v22, v102, 16, 1
	v_lshrrev_b32_e32 v2, 16, v2
	v_add3_u32 v22, v102, v22, s93
	v_and_or_b32 v89, v22, s33, v2
	v_or_b32_e32 v2, s4, v83
	v_lshlrev_b32_e32 v2, 11, v2
	v_lshl_add_u64 v[104:105], v[20:21], 0, v[2:3]
	v_bfe_u32 v2, v91, 16, 1
	v_add3_u32 v2, v91, v2, s93
	v_bfe_u32 v22, v23, 16, 1
	v_lshrrev_b32_e32 v2, 16, v2
	v_add3_u32 v22, v23, v22, s93
	global_store_dwordx4 v[104:105], v[86:89], off
	s_nop 1
	v_and_or_b32 v86, v22, s33, v2
	v_bfe_u32 v2, v93, 16, 1
	v_add3_u32 v2, v93, v2, s93
	v_bfe_u32 v22, v95, 16, 1
	v_lshrrev_b32_e32 v2, 16, v2
	v_add3_u32 v22, v95, v22, s93
	v_and_or_b32 v87, v22, s33, v2
	v_bfe_u32 v2, v97, 16, 1
	v_add3_u32 v2, v97, v2, s93
	v_bfe_u32 v22, v99, 16, 1
	v_lshrrev_b32_e32 v2, 16, v2
	v_add3_u32 v22, v99, v22, s93
	v_and_or_b32 v88, v22, s33, v2
	v_bfe_u32 v2, v101, 16, 1
	v_add3_u32 v2, v101, v2, s93
	v_bfe_u32 v22, v103, 16, 1
	v_lshrrev_b32_e32 v2, 16, v2
	v_add3_u32 v22, v103, v22, s93
	v_and_or_b32 v89, v22, s33, v2
	v_or_b32_e32 v2, s4, v84
	v_lshlrev_b32_e32 v2, 11, v2
	v_lshl_add_u64 v[20:21], v[20:21], 0, v[2:3]
	global_store_dwordx4 v[20:21], v[86:89], off
	s_waitcnt lgkmcnt(0)

.LBB0_1952:
	s_load_dwordx4 s[4:7], s[62:63], 0x40
	v_lshlrev_b32_e32 v2, 2, v4
	s_waitcnt lgkmcnt(0)
	s_add_u32 s30, s4, 0x1000
	s_addc_u32 s31, s5, 0
	s_ashr_i32 s26, s29, 31
	s_lshr_b32 s26, s26, 26
	s_add_i32 s26, s29, s26
	s_and_b32 s28, s26, 0xffffffc0
	s_sub_i32 s26, s29, s28
	s_lshl_b32 s26, s26, 5
	s_ashr_i32 s27, s26, 31
	s_lshl_b64 s[40:41], s[26:27], 2
	s_add_u32 s6, s6, s40
	v_or_b32_e32 v22, s28, v1
	s_addc_u32 s7, s7, s41
	v_ashrrev_i32_e32 v23, 31, v22
	v_lshl_add_u64 v[20:21], s[6:7], 0, v[2:3]
	s_mov_b64 s[6:7], 0x800000
	v_lshl_add_u64 v[20:21], v[20:21], 0, s[6:7]
	v_lshlrev_b64 v[86:87], 13, v[22:23]
	v_lshl_add_u64 v[86:87], v[20:21], 0, v[86:87]
	s_cmp_eq_u64 s[4:5], 0
	s_cbranch_scc1 .Lladder_ng_g9
	global_load_dword v88, v[86:87], off
	v_lshl_add_u64 v[22:23], v[22:23], 2, s[30:31]
	global_load_dword v89, v[22:23], off
	v_or_b32_e32 v22, s28, v25
	v_ashrrev_i32_e32 v23, 31, v22
	v_lshlrev_b64 v[86:87], 13, v[22:23]
	v_lshl_add_u64 v[86:87], v[20:21], 0, v[86:87]
	global_load_dword v90, v[86:87], off
	v_lshl_add_u64 v[22:23], v[22:23], 2, s[30:31]
	global_load_dword v91, v[22:23], off
	v_or_b32_e32 v22, s28, v27
	v_ashrrev_i32_e32 v23, 31, v22
	v_lshlrev_b64 v[86:87], 13, v[22:23]
	v_lshl_add_u64 v[86:87], v[20:21], 0, v[86:87]
	global_load_dword v92, v[86:87], off
	v_lshl_add_u64 v[22:23], v[22:23], 2, s[30:31]
	global_load_dword v93, v[22:23], off
	v_or_b32_e32 v22, s28, v29
	v_ashrrev_i32_e32 v23, 31, v22
	v_lshlrev_b64 v[86:87], 13, v[22:23]
	v_lshl_add_u64 v[86:87], v[20:21], 0, v[86:87]
	global_load_dword v94, v[86:87], off
	v_lshl_add_u64 v[22:23], v[22:23], 2, s[30:31]
	global_load_dword v95, v[22:23], off
	v_or_b32_e32 v22, s28, v31
	v_ashrrev_i32_e32 v23, 31, v22
	v_lshlrev_b64 v[86:87], 13, v[22:23]
	v_lshl_add_u64 v[86:87], v[20:21], 0, v[86:87]
	global_load_dword v96, v[86:87], off
	v_lshl_add_u64 v[22:23], v[22:23], 2, s[30:31]
	global_load_dword v97, v[22:23], off
	v_or_b32_e32 v22, s28, v33
	v_ashrrev_i32_e32 v23, 31, v22
	v_lshlrev_b64 v[86:87], 13, v[22:23]
	v_lshl_add_u64 v[86:87], v[20:21], 0, v[86:87]
	global_load_dword v98, v[86:87], off
	v_lshl_add_u64 v[22:23], v[22:23], 2, s[30:31]
	global_load_dword v99, v[22:23], off
	v_or_b32_e32 v22, s28, v35
	v_ashrrev_i32_e32 v23, 31, v22
	v_lshlrev_b64 v[86:87], 13, v[22:23]
	v_lshl_add_u64 v[86:87], v[20:21], 0, v[86:87]
	global_load_dword v100, v[86:87], off
	v_lshl_add_u64 v[22:23], v[22:23], 2, s[30:31]
	global_load_dword v101, v[22:23], off
	v_or_b32_e32 v22, s28, v37
	v_ashrrev_i32_e32 v23, 31, v22
	v_lshlrev_b64 v[86:87], 13, v[22:23]
	v_lshl_add_u64 v[86:87], v[20:21], 0, v[86:87]
	global_load_dword v102, v[86:87], off
	v_lshl_add_u64 v[22:23], v[22:23], 2, s[30:31]
	global_load_dword v103, v[22:23], off
	v_or_b32_e32 v22, s28, v39
	v_ashrrev_i32_e32 v23, 31, v22
	v_lshlrev_b64 v[86:87], 13, v[22:23]
	v_lshl_add_u64 v[86:87], v[20:21], 0, v[86:87]
	global_load_dword v104, v[86:87], off
	v_lshl_add_u64 v[22:23], v[22:23], 2, s[30:31]
	global_load_dword v105, v[22:23], off
	v_or_b32_e32 v22, s28, v41
	v_ashrrev_i32_e32 v23, 31, v22
	v_lshlrev_b64 v[86:87], 13, v[22:23]
	v_lshl_add_u64 v[86:87], v[20:21], 0, v[86:87]
	global_load_dword v148, v[86:87], off
	v_lshl_add_u64 v[22:23], v[22:23], 2, s[30:31]
	global_load_dword v149, v[22:23], off
	v_or_b32_e32 v22, s28, v43
	v_ashrrev_i32_e32 v23, 31, v22
	v_lshlrev_b64 v[86:87], 13, v[22:23]
	v_lshl_add_u64 v[86:87], v[20:21], 0, v[86:87]
	global_load_dword v150, v[86:87], off
	v_lshl_add_u64 v[22:23], v[22:23], 2, s[30:31]
	global_load_dword v151, v[22:23], off
	v_or_b32_e32 v22, s28, v45
	v_ashrrev_i32_e32 v23, 31, v22
	v_lshlrev_b64 v[86:87], 13, v[22:23]
	v_lshl_add_u64 v[86:87], v[20:21], 0, v[86:87]
	global_load_dword v152, v[86:87], off
	v_lshl_add_u64 v[22:23], v[22:23], 2, s[30:31]
	global_load_dword v153, v[22:23], off
	v_or_b32_e32 v22, s28, v47
	v_ashrrev_i32_e32 v23, 31, v22
	v_lshlrev_b64 v[86:87], 13, v[22:23]
	v_lshl_add_u64 v[86:87], v[20:21], 0, v[86:87]
	global_load_dword v154, v[86:87], off
	v_lshl_add_u64 v[22:23], v[22:23], 2, s[30:31]
	global_load_dword v155, v[22:23], off
	v_or_b32_e32 v22, s28, v49
	v_ashrrev_i32_e32 v23, 31, v22
	v_lshlrev_b64 v[86:87], 13, v[22:23]
	v_lshl_add_u64 v[86:87], v[20:21], 0, v[86:87]
	global_load_dword v156, v[86:87], off
	v_lshl_add_u64 v[22:23], v[22:23], 2, s[30:31]
	global_load_dword v157, v[22:23], off
	v_or_b32_e32 v22, s28, v51
	v_ashrrev_i32_e32 v23, 31, v22
	v_lshlrev_b64 v[86:87], 13, v[22:23]
	v_lshl_add_u64 v[86:87], v[20:21], 0, v[86:87]
	global_load_dword v158, v[86:87], off
	v_lshl_add_u64 v[22:23], v[22:23], 2, s[30:31]
	global_load_dword v159, v[22:23], off
	v_or_b32_e32 v22, s28, v53
	v_ashrrev_i32_e32 v23, 31, v22
	v_lshlrev_b64 v[86:87], 13, v[22:23]
	v_lshl_add_u64 v[86:87], v[20:21], 0, v[86:87]
	global_load_dword v160, v[86:87], off
	v_lshl_add_u64 v[22:23], v[22:23], 2, s[30:31]
	global_load_dword v161, v[22:23], off
	v_or_b32_e32 v22, s28, v55
	v_ashrrev_i32_e32 v23, 31, v22
	v_lshlrev_b64 v[86:87], 13, v[22:23]
	v_lshl_add_u64 v[86:87], v[20:21], 0, v[86:87]
	global_load_dword v162, v[86:87], off
	v_lshl_add_u64 v[22:23], v[22:23], 2, s[30:31]
	global_load_dword v163, v[22:23], off
	v_or_b32_e32 v22, s28, v57
	v_ashrrev_i32_e32 v23, 31, v22
	v_lshlrev_b64 v[86:87], 13, v[22:23]
	v_lshl_add_u64 v[86:87], v[20:21], 0, v[86:87]
	global_load_dword v165, v[86:87], off
	v_lshl_add_u64 v[22:23], v[22:23], 2, s[30:31]
	global_load_dword v166, v[22:23], off
	v_or_b32_e32 v22, s28, v59
	v_ashrrev_i32_e32 v23, 31, v22
	v_lshlrev_b64 v[86:87], 13, v[22:23]
	v_lshl_add_u64 v[86:87], v[20:21], 0, v[86:87]
	global_load_dword v167, v[86:87], off
	v_lshl_add_u64 v[22:23], v[22:23], 2, s[30:31]
	global_load_dword v168, v[22:23], off
	v_or_b32_e32 v22, s28, v61
	v_ashrrev_i32_e32 v23, 31, v22
	v_lshlrev_b64 v[86:87], 13, v[22:23]
	v_lshl_add_u64 v[86:87], v[20:21], 0, v[86:87]
	global_load_dword v169, v[86:87], off
	v_lshl_add_u64 v[22:23], v[22:23], 2, s[30:31]
	global_load_dword v170, v[22:23], off
	v_or_b32_e32 v22, s28, v63
	v_ashrrev_i32_e32 v23, 31, v22
	v_lshlrev_b64 v[86:87], 13, v[22:23]
	v_lshl_add_u64 v[86:87], v[20:21], 0, v[86:87]
	global_load_dword v171, v[86:87], off
	v_lshl_add_u64 v[22:23], v[22:23], 2, s[30:31]
	global_load_dword v172, v[22:23], off
	v_or_b32_e32 v22, s28, v65
	v_ashrrev_i32_e32 v23, 31, v22
	v_lshlrev_b64 v[86:87], 13, v[22:23]
	v_lshl_add_u64 v[86:87], v[20:21], 0, v[86:87]
	global_load_dword v173, v[86:87], off
	v_lshl_add_u64 v[22:23], v[22:23], 2, s[30:31]
	global_load_dword v174, v[22:23], off
	v_or_b32_e32 v22, s28, v67
	v_ashrrev_i32_e32 v23, 31, v22
	v_lshlrev_b64 v[86:87], 13, v[22:23]
	v_lshl_add_u64 v[86:87], v[20:21], 0, v[86:87]
	global_load_dword v175, v[86:87], off
	v_lshl_add_u64 v[22:23], v[22:23], 2, s[30:31]
	global_load_dword v176, v[22:23], off
	v_or_b32_e32 v22, s28, v69
	v_ashrrev_i32_e32 v23, 31, v22
	v_lshlrev_b64 v[86:87], 13, v[22:23]
	v_lshl_add_u64 v[86:87], v[20:21], 0, v[86:87]
	global_load_dword v177, v[86:87], off
	v_lshl_add_u64 v[22:23], v[22:23], 2, s[30:31]
	global_load_dword v178, v[22:23], off
	v_or_b32_e32 v22, s28, v71
	v_ashrrev_i32_e32 v23, 31, v22
	v_lshlrev_b64 v[86:87], 13, v[22:23]
	v_lshl_add_u64 v[86:87], v[20:21], 0, v[86:87]
	global_load_dword v179, v[86:87], off
	v_lshl_add_u64 v[22:23], v[22:23], 2, s[30:31]
	global_load_dword v180, v[22:23], off
	v_or_b32_e32 v22, s28, v73
	v_ashrrev_i32_e32 v23, 31, v22
	v_lshlrev_b64 v[86:87], 13, v[22:23]
	v_lshl_add_u64 v[86:87], v[20:21], 0, v[86:87]
	global_load_dword v181, v[86:87], off
	v_lshl_add_u64 v[22:23], v[22:23], 2, s[30:31]
	global_load_dword v182, v[22:23], off
	v_or_b32_e32 v22, s28, v74
	v_ashrrev_i32_e32 v23, 31, v22
	v_lshlrev_b64 v[86:87], 13, v[22:23]
	v_lshl_add_u64 v[86:87], v[20:21], 0, v[86:87]
	global_load_dword v183, v[86:87], off
	v_lshl_add_u64 v[22:23], v[22:23], 2, s[30:31]
	global_load_dword v184, v[22:23], off
	v_or_b32_e32 v22, s28, v75
	v_ashrrev_i32_e32 v23, 31, v22
	v_lshlrev_b64 v[86:87], 13, v[22:23]
	v_lshl_add_u64 v[86:87], v[20:21], 0, v[86:87]
	global_load_dword v185, v[86:87], off
	v_lshl_add_u64 v[22:23], v[22:23], 2, s[30:31]
	global_load_dword v186, v[22:23], off
	v_or_b32_e32 v22, s28, v76
	v_ashrrev_i32_e32 v23, 31, v22
	v_lshlrev_b64 v[86:87], 13, v[22:23]
	v_lshl_add_u64 v[86:87], v[20:21], 0, v[86:87]
	global_load_dword v187, v[86:87], off
	v_lshl_add_u64 v[22:23], v[22:23], 2, s[30:31]
	global_load_dword v188, v[22:23], off
	v_or_b32_e32 v22, s28, v77
	v_ashrrev_i32_e32 v23, 31, v22
	v_lshlrev_b64 v[86:87], 13, v[22:23]
	v_lshl_add_u64 v[86:87], v[20:21], 0, v[86:87]
	global_load_dword v189, v[86:87], off
	v_lshl_add_u64 v[22:23], v[22:23], 2, s[30:31]
	global_load_dword v190, v[22:23], off
	v_or_b32_e32 v22, s28, v78
	v_ashrrev_i32_e32 v23, 31, v22
	v_lshlrev_b64 v[86:87], 13, v[22:23]
	v_lshl_add_u64 v[86:87], v[20:21], 0, v[86:87]
	global_load_dword v191, v[86:87], off
	v_lshl_add_u64 v[22:23], v[22:23], 2, s[30:31]
	global_load_dword v192, v[22:23], off
	v_or_b32_e32 v22, s28, v79
	v_ashrrev_i32_e32 v23, 31, v22
	v_lshlrev_b64 v[86:87], 13, v[22:23]
	v_lshl_add_u64 v[20:21], v[20:21], 0, v[86:87]
	global_load_dword v193, v[20:21], off
	v_lshl_add_u64 v[22:23], v[22:23], 2, s[30:31]
	global_load_dword v194, v[22:23], off
	s_waitcnt vmcnt(0)
	v_mul_f32_e32 v88, v88, v89
	v_add_u32_e32 v195, v5, v24
	ds_write_b32 v195, v88
	v_mul_f32_e32 v90, v90, v91
	v_add_u32_e32 v196, v5, v26
	ds_write_b32 v196, v90
	v_mul_f32_e32 v92, v92, v93
	v_add_u32_e32 v197, v5, v28
	ds_write_b32 v197, v92
	v_mul_f32_e32 v94, v94, v95
	v_add_u32_e32 v198, v5, v30
	ds_write_b32 v198, v94
	v_mul_f32_e32 v96, v96, v97
	v_add_u32_e32 v199, v5, v32
	ds_write_b32 v199, v96
	v_mul_f32_e32 v98, v98, v99
	v_add_u32_e32 v200, v5, v34
	ds_write_b32 v200, v98
	v_mul_f32_e32 v100, v100, v101
	v_add_u32_e32 v201, v5, v36
	ds_write_b32 v201, v100
	v_mul_f32_e32 v102, v102, v103
	v_add_u32_e32 v202, v5, v38
	ds_write_b32 v202, v102
	v_mul_f32_e32 v104, v104, v105
	v_add_u32_e32 v203, v5, v40
	ds_write_b32 v203, v104
	v_mul_f32_e32 v148, v148, v149
	v_add_u32_e32 v204, v5, v42
	ds_write_b32 v204, v148
	v_mul_f32_e32 v150, v150, v151
	v_add_u32_e32 v205, v5, v44
	ds_write_b32 v205, v150
	v_mul_f32_e32 v152, v152, v153
	v_add_u32_e32 v206, v5, v46
	ds_write_b32 v206, v152
	v_mul_f32_e32 v154, v154, v155
	v_add_u32_e32 v207, v5, v48
	ds_write_b32 v207, v154
	v_mul_f32_e32 v156, v156, v157
	v_add_u32_e32 v210, v5, v50
	ds_write_b32 v210, v156
	v_mul_f32_e32 v158, v158, v159
	v_add_u32_e32 v211, v5, v52
	ds_write_b32 v211, v158
	v_mul_f32_e32 v160, v160, v161
	v_add_u32_e32 v212, v5, v54
	ds_write_b32 v212, v160
	v_mul_f32_e32 v162, v162, v163
	v_add_u32_e32 v213, v5, v56
	ds_write_b32 v213, v162
	v_mul_f32_e32 v165, v165, v166
	v_add_u32_e32 v217, v5, v58
	ds_write_b32 v217, v165
	v_mul_f32_e32 v167, v167, v168
	v_add_u32_e32 v218, v5, v60
	ds_write_b32 v218, v167
	v_mul_f32_e32 v169, v169, v170
	v_add_u32_e32 v219, v5, v62
	ds_write_b32 v219, v169
	v_mul_f32_e32 v171, v171, v172
	v_add_u32_e32 v220, v5, v64
	ds_write_b32 v220, v171
	v_mul_f32_e32 v173, v173, v174
	v_add_u32_e32 v221, v5, v66
	ds_write_b32 v221, v173
	v_mul_f32_e32 v175, v175, v176
	v_add_u32_e32 v222, v5, v68
	ds_write_b32 v222, v175
	v_mul_f32_e32 v177, v177, v178
	v_add_u32_e32 v223, v5, v70
	ds_write_b32 v223, v177
	v_mul_f32_e32 v179, v179, v180
	v_add_u32_e32 v224, v5, v72
	ds_write_b32 v224, v179
	v_mul_f32_e32 v181, v181, v182
	ds_write_b32 v224, v181 offset:264
	v_mul_f32_e32 v183, v183, v184
	ds_write_b32 v224, v183 offset:528
	v_mul_f32_e32 v185, v185, v186
	ds_write_b32 v224, v185 offset:792
	v_mul_f32_e32 v187, v187, v188
	ds_write_b32 v224, v187 offset:1056
	v_mul_f32_e32 v189, v189, v190
	ds_write_b32 v224, v189 offset:1320
	v_mul_f32_e32 v191, v191, v192
	ds_write_b32 v224, v191 offset:1584
	v_mul_f32_e32 v193, v193, v194
	v_mov_b32_e32 v2, v224
	v_mov_b32_e32 v20, v193
	s_branch .LBB0_1667
.Lladder_ng_g9:
	global_load_dword v88, v[86:87], off
	v_or_b32_e32 v22, s28, v25
	v_ashrrev_i32_e32 v23, 31, v22
	v_lshlrev_b64 v[86:87], 13, v[22:23]
	v_lshl_add_u64 v[86:87], v[20:21], 0, v[86:87]
	global_load_dword v89, v[86:87], off
	v_or_b32_e32 v22, s28, v27
	v_ashrrev_i32_e32 v23, 31, v22
	v_lshlrev_b64 v[86:87], 13, v[22:23]
	v_lshl_add_u64 v[86:87], v[20:21], 0, v[86:87]
	global_load_dword v90, v[86:87], off
	v_or_b32_e32 v22, s28, v29
	v_ashrrev_i32_e32 v23, 31, v22
	v_lshlrev_b64 v[86:87], 13, v[22:23]
	v_lshl_add_u64 v[86:87], v[20:21], 0, v[86:87]
	global_load_dword v91, v[86:87], off
	v_or_b32_e32 v22, s28, v31
	v_ashrrev_i32_e32 v23, 31, v22
	v_lshlrev_b64 v[86:87], 13, v[22:23]
	v_lshl_add_u64 v[86:87], v[20:21], 0, v[86:87]
	global_load_dword v92, v[86:87], off
	v_or_b32_e32 v22, s28, v33
	v_ashrrev_i32_e32 v23, 31, v22
	v_lshlrev_b64 v[86:87], 13, v[22:23]
	v_lshl_add_u64 v[86:87], v[20:21], 0, v[86:87]
	global_load_dword v93, v[86:87], off
	v_or_b32_e32 v22, s28, v35
	v_ashrrev_i32_e32 v23, 31, v22
	v_lshlrev_b64 v[86:87], 13, v[22:23]
	v_lshl_add_u64 v[86:87], v[20:21], 0, v[86:87]
	global_load_dword v94, v[86:87], off
	v_or_b32_e32 v22, s28, v37
	v_ashrrev_i32_e32 v23, 31, v22
	v_lshlrev_b64 v[86:87], 13, v[22:23]
	v_lshl_add_u64 v[86:87], v[20:21], 0, v[86:87]
	global_load_dword v95, v[86:87], off
	v_or_b32_e32 v22, s28, v39
	v_ashrrev_i32_e32 v23, 31, v22
	v_lshlrev_b64 v[86:87], 13, v[22:23]
	v_lshl_add_u64 v[86:87], v[20:21], 0, v[86:87]
	global_load_dword v96, v[86:87], off
	v_or_b32_e32 v22, s28, v41
	v_ashrrev_i32_e32 v23, 31, v22
	v_lshlrev_b64 v[86:87], 13, v[22:23]
	v_lshl_add_u64 v[86:87], v[20:21], 0, v[86:87]
	global_load_dword v97, v[86:87], off
	v_or_b32_e32 v22, s28, v43
	v_ashrrev_i32_e32 v23, 31, v22
	v_lshlrev_b64 v[86:87], 13, v[22:23]
	v_lshl_add_u64 v[86:87], v[20:21], 0, v[86:87]
	global_load_dword v98, v[86:87], off
	v_or_b32_e32 v22, s28, v45
	v_ashrrev_i32_e32 v23, 31, v22
	v_lshlrev_b64 v[86:87], 13, v[22:23]
	v_lshl_add_u64 v[86:87], v[20:21], 0, v[86:87]
	global_load_dword v99, v[86:87], off
	v_or_b32_e32 v22, s28, v47
	v_ashrrev_i32_e32 v23, 31, v22
	v_lshlrev_b64 v[86:87], 13, v[22:23]
	v_lshl_add_u64 v[86:87], v[20:21], 0, v[86:87]
	global_load_dword v100, v[86:87], off
	v_or_b32_e32 v22, s28, v49
	v_ashrrev_i32_e32 v23, 31, v22
	v_lshlrev_b64 v[86:87], 13, v[22:23]
	v_lshl_add_u64 v[86:87], v[20:21], 0, v[86:87]
	global_load_dword v101, v[86:87], off
	v_or_b32_e32 v22, s28, v51
	v_ashrrev_i32_e32 v23, 31, v22
	v_lshlrev_b64 v[86:87], 13, v[22:23]
	v_lshl_add_u64 v[86:87], v[20:21], 0, v[86:87]
	global_load_dword v102, v[86:87], off
	v_or_b32_e32 v22, s28, v53
	v_ashrrev_i32_e32 v23, 31, v22
	v_lshlrev_b64 v[86:87], 13, v[22:23]
	v_lshl_add_u64 v[86:87], v[20:21], 0, v[86:87]
	global_load_dword v103, v[86:87], off
	v_or_b32_e32 v22, s28, v55
	v_ashrrev_i32_e32 v23, 31, v22
	v_lshlrev_b64 v[86:87], 13, v[22:23]
	v_lshl_add_u64 v[86:87], v[20:21], 0, v[86:87]
	global_load_dword v104, v[86:87], off
	v_or_b32_e32 v22, s28, v57
	v_ashrrev_i32_e32 v23, 31, v22
	v_lshlrev_b64 v[86:87], 13, v[22:23]
	v_lshl_add_u64 v[86:87], v[20:21], 0, v[86:87]
	global_load_dword v105, v[86:87], off
	v_or_b32_e32 v22, s28, v59
	v_ashrrev_i32_e32 v23, 31, v22
	v_lshlrev_b64 v[86:87], 13, v[22:23]
	v_lshl_add_u64 v[86:87], v[20:21], 0, v[86:87]
	global_load_dword v148, v[86:87], off
	v_or_b32_e32 v22, s28, v61
	v_ashrrev_i32_e32 v23, 31, v22
	v_lshlrev_b64 v[86:87], 13, v[22:23]
	v_lshl_add_u64 v[86:87], v[20:21], 0, v[86:87]
	global_load_dword v149, v[86:87], off
	v_or_b32_e32 v22, s28, v63
	v_ashrrev_i32_e32 v23, 31, v22
	v_lshlrev_b64 v[86:87], 13, v[22:23]
	v_lshl_add_u64 v[86:87], v[20:21], 0, v[86:87]
	global_load_dword v150, v[86:87], off
	v_or_b32_e32 v22, s28, v65
	v_ashrrev_i32_e32 v23, 31, v22
	v_lshlrev_b64 v[86:87], 13, v[22:23]
	v_lshl_add_u64 v[86:87], v[20:21], 0, v[86:87]
	global_load_dword v151, v[86:87], off
	v_or_b32_e32 v22, s28, v67
	v_ashrrev_i32_e32 v23, 31, v22
	v_lshlrev_b64 v[86:87], 13, v[22:23]
	v_lshl_add_u64 v[86:87], v[20:21], 0, v[86:87]
	global_load_dword v152, v[86:87], off
	v_or_b32_e32 v22, s28, v69
	v_ashrrev_i32_e32 v23, 31, v22
	v_lshlrev_b64 v[86:87], 13, v[22:23]
	v_lshl_add_u64 v[86:87], v[20:21], 0, v[86:87]
	global_load_dword v153, v[86:87], off
	v_or_b32_e32 v22, s28, v71
	v_ashrrev_i32_e32 v23, 31, v22
	v_lshlrev_b64 v[86:87], 13, v[22:23]
	v_lshl_add_u64 v[86:87], v[20:21], 0, v[86:87]
	global_load_dword v154, v[86:87], off
	v_or_b32_e32 v22, s28, v73
	v_ashrrev_i32_e32 v23, 31, v22
	v_lshlrev_b64 v[86:87], 13, v[22:23]
	v_lshl_add_u64 v[86:87], v[20:21], 0, v[86:87]
	global_load_dword v155, v[86:87], off
	v_or_b32_e32 v22, s28, v74
	v_ashrrev_i32_e32 v23, 31, v22
	v_lshlrev_b64 v[86:87], 13, v[22:23]
	v_lshl_add_u64 v[86:87], v[20:21], 0, v[86:87]
	global_load_dword v156, v[86:87], off
	v_or_b32_e32 v22, s28, v75
	v_ashrrev_i32_e32 v23, 31, v22
	v_lshlrev_b64 v[86:87], 13, v[22:23]
	v_lshl_add_u64 v[86:87], v[20:21], 0, v[86:87]
	global_load_dword v157, v[86:87], off
	v_or_b32_e32 v22, s28, v76
	v_ashrrev_i32_e32 v23, 31, v22
	v_lshlrev_b64 v[86:87], 13, v[22:23]
	v_lshl_add_u64 v[86:87], v[20:21], 0, v[86:87]
	global_load_dword v158, v[86:87], off
	v_or_b32_e32 v22, s28, v77
	v_ashrrev_i32_e32 v23, 31, v22
	v_lshlrev_b64 v[86:87], 13, v[22:23]
	v_lshl_add_u64 v[86:87], v[20:21], 0, v[86:87]
	global_load_dword v159, v[86:87], off
	v_or_b32_e32 v22, s28, v78
	v_ashrrev_i32_e32 v23, 31, v22
	v_lshlrev_b64 v[86:87], 13, v[22:23]
	v_lshl_add_u64 v[86:87], v[20:21], 0, v[86:87]
	global_load_dword v160, v[86:87], off
	v_or_b32_e32 v22, s28, v79
	v_ashrrev_i32_e32 v23, 31, v22
	v_lshlrev_b64 v[86:87], 13, v[22:23]
	v_lshl_add_u64 v[20:21], v[20:21], 0, v[86:87]
	global_load_dword v161, v[20:21], off
	s_waitcnt vmcnt(0)
	v_add_u32_e32 v162, v5, v24
	ds_write_b32 v162, v88
	v_add_u32_e32 v163, v5, v26
	ds_write_b32 v163, v89
	v_add_u32_e32 v165, v5, v28
	ds_write_b32 v165, v90
	v_add_u32_e32 v166, v5, v30
	ds_write_b32 v166, v91
	v_add_u32_e32 v167, v5, v32
	ds_write_b32 v167, v92
	v_add_u32_e32 v168, v5, v34
	ds_write_b32 v168, v93
	v_add_u32_e32 v169, v5, v36
	ds_write_b32 v169, v94
	v_add_u32_e32 v170, v5, v38
	ds_write_b32 v170, v95
	v_add_u32_e32 v171, v5, v40
	ds_write_b32 v171, v96
	v_add_u32_e32 v172, v5, v42
	ds_write_b32 v172, v97
	v_add_u32_e32 v173, v5, v44
	ds_write_b32 v173, v98
	v_add_u32_e32 v174, v5, v46
	ds_write_b32 v174, v99
	v_add_u32_e32 v175, v5, v48
	ds_write_b32 v175, v100
	v_add_u32_e32 v176, v5, v50
	ds_write_b32 v176, v101
	v_add_u32_e32 v177, v5, v52
	ds_write_b32 v177, v102
	v_add_u32_e32 v178, v5, v54
	ds_write_b32 v178, v103
	v_add_u32_e32 v179, v5, v56
	ds_write_b32 v179, v104
	v_add_u32_e32 v180, v5, v58
	ds_write_b32 v180, v105
	v_add_u32_e32 v181, v5, v60
	ds_write_b32 v181, v148
	v_add_u32_e32 v182, v5, v62
	ds_write_b32 v182, v149
	v_add_u32_e32 v183, v5, v64
	ds_write_b32 v183, v150
	v_add_u32_e32 v184, v5, v66
	ds_write_b32 v184, v151
	v_add_u32_e32 v185, v5, v68
	ds_write_b32 v185, v152
	v_add_u32_e32 v186, v5, v70
	ds_write_b32 v186, v153
	v_add_u32_e32 v187, v5, v72
	ds_write_b32 v187, v154
	ds_write_b32 v187, v155 offset:264
	ds_write_b32 v187, v156 offset:528
	ds_write_b32 v187, v157 offset:792
	ds_write_b32 v187, v158 offset:1056
	ds_write_b32 v187, v159 offset:1320
	ds_write_b32 v187, v160 offset:1584
	v_mov_b32_e32 v2, v187
	v_mov_b32_e32 v20, v161
	s_branch .LBB0_1667
